# hand-written weight conversion routine (lean, 2-buffer pipeline) replacing compiler convert loops; 40 idle WGs of G1/G5 last round convert 2560 items each of next-layer weights
# speedup vs baseline: 1.0047x; 1.0047x over previous
.LBB0_15:
	s_lshl_b32 s66, s3, 3
	s_cmp_lt_i32 s62, 1
	s_cselect_b64 s[4:5], -1, 0
	s_cmp_gt_i32 s63, 0
	s_cselect_b64 s[6:7], -1, 0
	s_and_b64 s[10:11], s[4:5], s[6:7]
	s_andn2_b64 vcc, exec, s[10:11]
	s_cbranch_vccnz .LBB0_240
	s_mov_b64 s[14:15], s[52:53]
	s_load_dwordx2 s[6:7], s[14:15], 0xc0
	s_lshr_b32 s34, s13, 6
	s_lshl_b32 s4, s54, 3
	v_bfe_u32 v1, v0, 3, 3
	s_add_i32 s12, s4, s34
	s_mov_b32 s98, 0
	s_branch .Lcv_entry
.Lcv_ret0:
	v_and_b32_e32 v162, 63, v0
	s_waitcnt lgkmcnt(0)

.LBB0_352:
	s_waitcnt vmcnt(0)
	v_readlane_b32 s60, v252, 49
	s_barrier
	s_mov_b32 s98, 3
	s_branch .Lcv_entry
.Lcv_ret3:
.LBB0_353:
	s_mul_i32 s4, s30, 10
	s_add_i32 s6, s4, 2
	s_cmp_lt_i32 s6, s63
	s_cselect_b64 s[4:5], -1, 0
	s_and_b64 s[0:1], s[0:1], s[4:5]
	s_andn2_b64 vcc, exec, s[0:1]
	s_cbranch_vccnz .LBB0_403
	s_waitcnt vmcnt(0)
	s_waitcnt vmcnt(0)
	s_barrier
	s_mov_b64 s[0:1], exec
	s_waitcnt lgkmcnt(0)
	v_readlane_b32 s8, v252, 43
	v_readlane_b32 s9, v252, 44
	s_and_b64 s[8:9], s[0:1], s[8:9]
	s_mov_b64 exec, s[8:9]
	s_cbranch_execz .LBB0_402
	v_readlane_b32 s8, v253, 2
	s_waitcnt vmcnt(0) expcnt(0) lgkmcnt(0)
	s_nop 0
	v_mov_b32_e32 v2, s8
	ds_read_b32 v4, v2
	ds_read_b32 v2, v2 offset:4
	s_waitcnt lgkmcnt(1)
	v_cmp_ne_u32_e32 vcc, 0, v4
	s_cbranch_vccnz .LBB0_370
	v_readlane_b32 s10, v253, 0
	v_readlane_b32 s11, v253, 1
	s_load_dwordx2 s[8:9], s[10:11], 0x4
	s_mov_b32 s16, 1
	s_waitcnt lgkmcnt(0)
	s_mul_i32 s14, s8, s3
	s_mul_i32 s14, s14, s9
	s_branch .LBB0_358

.LBB0_403:
	s_cmp_le_i32 s62, s6
	s_cselect_b64 s[0:1], -1, 0
	s_and_b64 s[0:1], s[0:1], s[4:5]
	v_writelane_b32 v252, s0, 53
	s_andn2_b64 vcc, exec, s[0:1]
	s_nop 0
	v_writelane_b32 v252, s1, 54
	s_cbranch_vccnz .LBB0_911
	s_cmp_eq_u32 s30, 3
	v_readlane_b32 s0, v253, 54
	s_cselect_b64 s[4:5], -1, 0
	v_readlane_b32 s1, v253, 55
	v_writelane_b32 v252, s4, 55
	s_waitcnt lgkmcnt(0)
	s_or_b64 s[8:9], s[0:1], s[4:5]
	v_readlane_b32 s0, v253, 3
	v_readlane_b32 s1, v253, 4
	v_writelane_b32 v252, s5, 56
	s_mul_i32 s4, s30, 0x4180
	s_load_dwordx2 s[60:61], s[0:1], 0xc0
	s_add_i32 s34, s4, 0x8300
	s_addk_i32 s4, 0x4180
	s_cmp_lg_u32 s30, 0
	s_cselect_b32 s4, s4, 0x1680
	v_readlane_b32 s5, v253, 53
	s_add_i32 s4, s4, s5
	s_waitcnt lgkmcnt(0)
	s_add_u32 s35, s60, 0x100000
	v_mov_b32_e32 v189, v0
	v_writelane_b32 v252, s4, 57
	s_addc_u32 s67, s61, 0
	s_and_b64 vcc, exec, s[8:9]
	v_readfirstlane_b32 s4, v189
	s_cbranch_vccnz .LBB0_621
	s_mov_b32 s98, 1
	s_branch .Lcv_entry
.Lcv_ret1:
.LBB0_620:
	s_barrier

.LBB0_697:
	s_or_b64 exec, exec, s[4:5]
	v_readlane_b32 s4, v253, 56
	v_readlane_b32 s8, v252, 55
	v_readlane_b32 s5, v253, 57
	v_readlane_b32 s9, v252, 56
	s_or_b64 s[4:5], s[8:9], s[4:5]
	s_andn2_b64 vcc, exec, s[4:5]
	v_readlane_b32 s60, v252, 49
	s_cbranch_vccz .LBB0_911
	s_barrier
	s_mov_b32 s98, 2
	s_branch .Lcv_entry
.Lcv_entry:
	s_waitcnt vmcnt(0) lgkmcnt(0)
	v_writelane_b32 v254, s4, 0
	v_writelane_b32 v254, s5, 1
	v_writelane_b32 v254, s6, 2
	v_writelane_b32 v254, s7, 3
	v_writelane_b32 v254, s8, 4
	v_writelane_b32 v254, s9, 5
	v_writelane_b32 v254, s10, 6
	v_writelane_b32 v254, s11, 7
	v_writelane_b32 v254, s12, 8
	v_writelane_b32 v254, s13, 9
	v_writelane_b32 v254, s14, 10
	v_writelane_b32 v254, s15, 11
	v_writelane_b32 v254, s16, 12
	v_writelane_b32 v254, s17, 13
	v_writelane_b32 v254, s18, 14
	v_writelane_b32 v254, s19, 15
	v_writelane_b32 v254, s20, 16
	v_writelane_b32 v254, s21, 17
	v_writelane_b32 v254, s22, 18
	v_writelane_b32 v254, s23, 19
	v_writelane_b32 v254, s24, 20
	v_writelane_b32 v254, s25, 21
	v_writelane_b32 v254, s26, 22
	v_writelane_b32 v254, s27, 23
	v_writelane_b32 v254, s28, 24
	v_writelane_b32 v254, s29, 25
	v_writelane_b32 v254, s30, 26
	v_writelane_b32 v254, s31, 27
	v_writelane_b32 v254, s32, 28
	v_writelane_b32 v254, s33, 29
	v_writelane_b32 v254, s34, 30
	v_writelane_b32 v254, s35, 31
	v_writelane_b32 v254, s36, 32
	v_writelane_b32 v254, s37, 33
	v_writelane_b32 v254, s38, 34
	v_writelane_b32 v254, s39, 35
	v_writelane_b32 v254, s40, 36
	v_writelane_b32 v254, s41, 37
	v_writelane_b32 v254, s42, 38
	v_writelane_b32 v254, s43, 39
	v_writelane_b32 v254, s44, 40
	v_writelane_b32 v254, s45, 41
	v_writelane_b32 v254, s46, 42
	v_writelane_b32 v254, s47, 43
	v_writelane_b32 v254, s48, 44
	v_writelane_b32 v254, s49, 45
	v_writelane_b32 v254, s50, 46
	v_writelane_b32 v254, s51, 47
	v_writelane_b32 v254, s52, 48
	v_writelane_b32 v254, s53, 49
	v_readlane_b32 s4, v253, 0
	v_readlane_b32 s5, v253, 1
	s_sub_u32 s4, s4, 0xd0
	s_subb_u32 s5, s5, 0
	s_load_dwordx2 s[6:7], s[4:5], 0xc0
	v_readfirstlane_b32 s29, v0
	s_lshr_b32 s29, s29, 6
	v_and_b32_e32 v8, 63, v0
	v_lshrrev_b32_e32 v9, 4, v8
	v_and_b32_e32 v10, 15, v8
	v_and_b32_e32 v11, 7, v8
	v_lshrrev_b32_e32 v13, 3, v8
	v_lshlrev_b32_e32 v4, 3, v9
	s_mul_i32 s31, s29, 0x2100
	v_mul_u32_u24_e32 v5, 0x108, v9
	v_lshlrev_b32_e32 v14, 4, v10
	v_add3_u32 v5, v5, v14, s31
	v_mul_u32_u24_e32 v6, 0x420, v11
	v_lshlrev_b32_e32 v15, 2, v13
	v_add3_u32 v6, v6, v15, s31
	v_lshlrev_b32_e32 v9, 1, v9
	v_lshlrev_b32_e32 v11, 4, v11
	s_and_b32 s31, s3, 7
	s_cmp_eq_u32 s31, 0
	s_cbranch_scc0 .Lcv_vcu_plain
	s_and_b32 s31, s2, 7
	s_lshr_b32 s32, s3, 3
	s_mul_i32 s31, s31, s32
	s_lshr_b32 s32, s2, 3
	s_add_u32 s31, s31, s32
	s_branch .Lcv_vcu_done
.Lcv_vcu_plain:
	s_mov_b32 s31, s2
.Lcv_vcu_done:
	s_lshl_b32 s31, s31, 3
	s_add_u32 s31, s31, s29
	s_cmp_eq_u32 s98, 0
	s_cbranch_scc0 .Lcv_site_p2
	s_mov_b32 s8, s31
	s_movk_i32 s9, 0x1680
	s_mov_b32 s10, s66
	s_branch .Lcv_go
.Lcv_site_p2:
	s_cmp_gt_u32 s98, 2
	s_cbranch_scc1 .Lcv_site_tail
	s_add_u32 s9, s30, 2
	s_mul_i32 s9, s9, 0x4180
	s_sub_u32 s8, s9, 0x4180
	s_cmp_eq_u32 s30, 0
	s_cselect_b32 s8, 0x1680, s8
	s_add_u32 s8, s8, s31
	s_mov_b32 s10, s66
	s_cmp_eq_u32 s3, 0x100
	s_cselect_b32 s32, 5120, 0
	s_sub_u32 s9, s9, s32
	s_branch .Lcv_go
.Lcv_site_tail:
	s_cmp_eq_u32 s3, 0x100
	s_cbranch_scc0 .Lcv_exit0
	s_cmp_lt_u32 s2, 216
	s_cbranch_scc1 .Lcv_exit0
	s_cmp_eq_u32 s98, 3
	s_cbranch_scc0 .Lcv_site_t5
	s_cmp_eq_u32 s30, 0
	s_cbranch_scc1 .Lcv_exit0
	s_add_u32 s9, s30, 1
	s_mul_i32 s9, s9, 0x4180
	s_sub_u32 s9, s9, 2560
	s_branch .Lcv_site_tc
.Lcv_site_t5:
	s_cmp_eq_u32 s30, 3
	s_cbranch_scc1 .Lcv_exit0
	s_add_u32 s9, s30, 2
	s_mul_i32 s9, s9, 0x4180
.Lcv_site_tc:
	s_sub_u32 s8, s9, 2560
	s_sub_u32 s32, s2, 216
	s_lshl_b32 s32, s32, 3
	s_add_u32 s32, s32, s29
	s_add_u32 s8, s8, s32
	s_movk_i32 s10, 0x140
.Lcv_go:
	s_waitcnt lgkmcnt(0)
	s_add_u32 s6, s6, 0x100000
	s_addc_u32 s7, s7, 0
	s_cmp_ge_u32 s8, s9
	s_cbranch_scc1 .Lcv_exit
	s_cmp_gt_u32 s98, 2
	s_cbranch_scc1 .Lcv_shallow
	s_mov_b32 s11, s8
	s_mov_b32 s12, 0
	s_mov_b32 s13, s11
	s_cmp_ge_u32 s13, 0x4180
	s_cbranch_scc0 .Lcv_d0_l
	s_sub_u32 s13, s13, 0x4180
	s_add_u32 s12, s12, 1
	s_cmp_ge_u32 s13, 0x4180
	s_cbranch_scc0 .Lcv_d0_l
	s_sub_u32 s13, s13, 0x4180
	s_add_u32 s12, s12, 1
	s_cmp_ge_u32 s13, 0x4180
	s_cbranch_scc0 .Lcv_d0_l
	s_sub_u32 s13, s13, 0x4180
	s_add_u32 s12, s12, 1
.Lcv_d0_l:
	s_mov_b32 s47, 0
	s_mov_b32 s43, 0
	s_mov_b32 s34, 0
	s_cmp_lt_u32 s13, 0x1600
	s_cbranch_scc1 .Lcv_d0_IN
	s_cmp_lt_u32 s13, 0x1680
	s_cbranch_scc1 .Lcv_d0_RI
	s_sub_u32 s13, s13, 0x1680
	s_cmp_lt_u32 s13, 512
	s_cbranch_scc1 .Lcv_d0_OA
	s_sub_u32 s13, s13, 512
	s_cmp_lt_u32 s13, 1024
	s_cbranch_scc1 .Lcv_d0_OB
	s_sub_u32 s13, s13, 1024
	s_cmp_lt_u32 s13, 1024
	s_cbranch_scc1 .Lcv_d0_O
	s_sub_u32 s13, s13, 1024
	s_cmp_lt_u32 s13, 0x1600
	s_cbranch_scc1 .Lcv_d0_GU
	s_sub_u32 s13, s13, 0x1600
	s_movk_i32 s29, 0xb0
	s_mov_b32 s31, 0x2c00000
	s_movk_i32 s25, 0x2000
	s_mov_b32 s32, 0x6c00000
	s_movk_i32 s38, 0x2c00
	s_branch .Lcv_d0_n32
.Lcv_d0_OA:
	s_movk_i32 s29, 0x38
	s_mov_b32 s31, 0x800000
	s_movk_i32 s25, 0x2000
	s_mov_b32 s32, 0x2c00000
	s_movk_i32 s38, 0x1800
	s_branch .Lcv_d0_n32
.Lcv_d0_OB:
	s_movk_i32 s29, 0x78
	s_mov_b32 s31, 0x1000000
	s_movk_i32 s25, 0x2000
	s_mov_b32 s32, 0x2c00000
	s_movk_i32 s38, 0x1800
	s_movk_i32 s43, 0x400
	s_branch .Lcv_d0_n32
.Lcv_d0_O:
	s_mov_b32 s29, 0x80
	s_mov_b32 s31, 0x1000000
	s_movk_i32 s25, 0x2000
	s_mov_b32 s32, 0x3800000
	s_movk_i32 s38, 0x1000
.Lcv_d0_n32:
	s_lshr_b32 s14, s13, 5
	s_and_b32 s35, s13, 31
	s_lshl_b32 s39, s35, 6
	s_branch .Lcv_d0_common
.Lcv_d0_RI:
	s_sub_u32 s13, s13, 0x1600
	s_lshr_b32 s48, s13, 6
	s_and_b32 s13, s13, 63
	s_lshr_b32 s49, s13, 2
	s_bfe_u32 s14, s13, 0x10001
	s_and_b32 s35, s13, 1
	s_lshl_b32 s29, s48, 4
	s_add_u32 s29, s29, 0x50
	s_mov_b32 s31, 0x100000
	s_movk_i32 s25, 0x200
	s_mov_b32 s32, 0x8200000
	s_movk_i32 s38, 0x100
	s_lshl_b32 s47, s49, 16
	s_lshl_b32 s39, s49, 8
	s_lshl_b32 s48, s48, 7
	s_add_u32 s39, s39, s48
	s_lshl_b32 s48, s35, 6
	s_add_u32 s39, s39, s48
	s_branch .Lcv_d0_common
.Lcv_d0_GU:
	s_mov_b32 s29, 0xa8
	s_mov_b32 s31, 0x5800000
	s_mov_b32 s25, 0xb000
	s_mov_b32 s32, 0x4000000
	s_movk_i32 s38, 0x1000
	s_mov_b32 s34, 0x98
	s_mul_hi_u32 s14, s13, 0x1745d18
	s_mul_i32 s35, s14, 176
	s_sub_u32 s35, s13, s35
	s_lshl_b32 s48, s35, 6
	s_cmp_ge_u32 s48, 0x1600
	s_cselect_b32 s49, 0x1600, 0
	s_cselect_b32 s50, 128, 0
	s_sub_u32 s48, s48, s49
	s_lshr_b32 s39, s48, 7
	s_lshl_b32 s39, s39, 8
	s_and_b32 s48, s48, 127
	s_add_u32 s39, s39, s48
	s_add_u32 s39, s39, s50
	s_branch .Lcv_d0_common
.Lcv_d0_IN:
	s_movk_i32 s29, 0x28
	s_mov_b32 s31, 0x5800000
	s_mov_b32 s25, 0xb000
	s_mov_b32 s32, 0
	s_movk_i32 s38, 0x1000
	s_mov_b32 s34, 0x88
	s_mul_hi_u32 s14, s13, 0x1745d18
	s_mul_i32 s35, s14, 176
	s_sub_u32 s35, s13, s35
	s_lshl_b32 s48, s35, 6
	s_cmp_lt_u32 s48, 0x400
	s_cbranch_scc0 .Lcv_d0_in1
	s_add_u32 s39, s48, 0x800
	s_branch .Lcv_d0_common
.Lcv_d0_in1:
	s_cmp_lt_u32 s48, 0xc00
	s_cbranch_scc0 .Lcv_d0_in2
	s_movk_i32 s49, 0x400
	s_cmp_ge_u32 s48, 0x800
	s_cselect_b32 s49, 0x800, s49
	s_cselect_b32 s50, 128, 0
	s_mov_b32 s51, 0
	s_branch .Lcv_d0_inq
.Lcv_d0_in2:
	s_cmp_lt_u32 s48, 0x1c00
	s_cbranch_scc0 .Lcv_d0_in3
	s_mov_b32 s39, s48
	s_branch .Lcv_d0_common
.Lcv_d0_in3:
	s_movk_i32 s49, 0x1c00
	s_cmp_ge_u32 s48, 0x2400
	s_cselect_b32 s49, 0x2400, s49
	s_cselect_b32 s50, 128, 0
	s_movk_i32 s51, 0x1c00
.Lcv_d0_inq:
	s_sub_u32 s48, s48, s49
	s_lshr_b32 s39, s48, 7
	s_lshl_b32 s39, s39, 8
	s_and_b32 s48, s48, 127
	s_add_u32 s39, s39, s48
	s_add_u32 s39, s39, s50
	s_add_u32 s39, s39, s51
.Lcv_d0_common:
	s_load_dwordx2 s[16:17], s[4:5], s29
	s_cmp_eq_u32 s34, 0
	s_cselect_b32 s28, 0, 1
	s_cbranch_scc1 .Lcv_d0_nog
	s_load_dwordx2 s[26:27], s[4:5], s34
.Lcv_d0_nog:
	s_mul_i32 s48, s12, s31
	s_mul_i32 s49, s14, s25
	s_lshl_b32 s49, s49, 6
	s_add_u32 s48, s48, s49
	s_lshl_b32 s49, s35, 8
	s_add_u32 s48, s48, s49
	s_add_u32 s48, s48, s47
	s_mul_i32 s49, s12, 0x8300000
	s_add_u32 s49, s49, s32
	s_mul_i32 s50, s39, s38
	s_add_u32 s49, s49, s50
	s_lshl_b32 s50, s14, 6
	s_add_u32 s50, s50, s43
	s_lshl_b32 s50, s50, 1
	s_add_u32 s49, s49, s50
	s_add_u32 s36, s6, s49
	s_addc_u32 s37, s7, 0
	s_lshl_b32 s50, s12, 13
	s_lshl_b32 s51, s14, 8
	s_add_u32 s50, s50, s51
	s_lshl_b32 s20, s25, 3
	s_waitcnt lgkmcnt(0)
	s_add_u32 s16, s16, s48
	s_addc_u32 s17, s17, 0
	s_add_u32 s26, s26, s50
	s_addc_u32 s27, s27, 0
	v_mad_u32_u24 v2, v9, s25, v14
	v_add_u32_e32 v3, s25, v2
	v_mad_u32_u24 v7, v13, s38, v11
	s_mov_b64 s[40:41], s[36:37]
	s_lshl_b32 s42, s38, 3
	s_cmp_eq_u32 s28, 0
	s_cbranch_scc1 .Lcv_l0_g1
	global_load_dwordx2 v[190:191], v4, s[26:27] offset:0
	global_load_dwordx2 v[192:193], v4, s[26:27] offset:32
	global_load_dwordx2 v[194:195], v4, s[26:27] offset:64
	global_load_dwordx2 v[196:197], v4, s[26:27] offset:96
	global_load_dwordx2 v[198:199], v4, s[26:27] offset:128
	global_load_dwordx2 v[200:201], v4, s[26:27] offset:160
	global_load_dwordx2 v[202:203], v4, s[26:27] offset:192
	global_load_dwordx2 v[204:205], v4, s[26:27] offset:224
	s_branch .Lcv_l0_gd
.Lcv_l0_g1:
	v_mov_b32_e32 v190, 1.0
	v_mov_b32_e32 v191, 1.0
	v_mov_b32_e32 v192, 1.0
	v_mov_b32_e32 v193, 1.0
	v_mov_b32_e32 v194, 1.0
	v_mov_b32_e32 v195, 1.0
	v_mov_b32_e32 v196, 1.0
	v_mov_b32_e32 v197, 1.0
	v_mov_b32_e32 v198, 1.0
	v_mov_b32_e32 v199, 1.0
	v_mov_b32_e32 v200, 1.0
	v_mov_b32_e32 v201, 1.0
	v_mov_b32_e32 v202, 1.0
	v_mov_b32_e32 v203, 1.0
	v_mov_b32_e32 v204, 1.0
	v_mov_b32_e32 v205, 1.0
.Lcv_l0_gd:
	global_load_dwordx4 v[36:39], v2, s[16:17]
	global_load_dwordx4 v[40:43], v3, s[16:17]
	s_add_u32 s16, s16, s20
	s_addc_u32 s17, s17, 0
	global_load_dwordx4 v[44:47], v2, s[16:17]
	global_load_dwordx4 v[48:51], v3, s[16:17]
	s_add_u32 s16, s16, s20
	s_addc_u32 s17, s17, 0
	global_load_dwordx4 v[52:55], v2, s[16:17]
	global_load_dwordx4 v[56:59], v3, s[16:17]
	s_add_u32 s16, s16, s20
	s_addc_u32 s17, s17, 0
	global_load_dwordx4 v[60:63], v2, s[16:17]
	global_load_dwordx4 v[64:67], v3, s[16:17]
	s_add_u32 s16, s16, s20
	s_addc_u32 s17, s17, 0
	global_load_dwordx4 v[68:71], v2, s[16:17]
	global_load_dwordx4 v[72:75], v3, s[16:17]
	s_add_u32 s16, s16, s20
	s_addc_u32 s17, s17, 0
	global_load_dwordx4 v[76:79], v2, s[16:17]
	global_load_dwordx4 v[80:83], v3, s[16:17]
	s_add_u32 s16, s16, s20
	s_addc_u32 s17, s17, 0
	global_load_dwordx4 v[84:87], v2, s[16:17]
	global_load_dwordx4 v[88:91], v3, s[16:17]
	s_add_u32 s16, s16, s20
	s_addc_u32 s17, s17, 0
	global_load_dwordx4 v[92:95], v2, s[16:17]
	global_load_dwordx4 v[96:99], v3, s[16:17]
	s_add_u32 s11, s8, s10
	s_cmp_ge_u32 s11, s9
	s_cbranch_scc1 .Lcv_only1
	s_mov_b32 s12, 0
	s_mov_b32 s13, s11
	s_cmp_ge_u32 s13, 0x4180
	s_cbranch_scc0 .Lcv_d1_l
	s_sub_u32 s13, s13, 0x4180
	s_add_u32 s12, s12, 1
	s_cmp_ge_u32 s13, 0x4180
	s_cbranch_scc0 .Lcv_d1_l
	s_sub_u32 s13, s13, 0x4180
	s_add_u32 s12, s12, 1
	s_cmp_ge_u32 s13, 0x4180
	s_cbranch_scc0 .Lcv_d1_l
	s_sub_u32 s13, s13, 0x4180
	s_add_u32 s12, s12, 1

.Lcv_d1_nog:
	s_mul_i32 s48, s12, s31
	s_mul_i32 s49, s14, s25
	s_lshl_b32 s49, s49, 6
	s_add_u32 s48, s48, s49
	s_lshl_b32 s49, s35, 8
	s_add_u32 s48, s48, s49
	s_add_u32 s48, s48, s47
	s_mul_i32 s49, s12, 0x8300000
	s_add_u32 s49, s49, s32
	s_mul_i32 s50, s39, s38
	s_add_u32 s49, s49, s50
	s_lshl_b32 s50, s14, 6
	s_add_u32 s50, s50, s43
	s_lshl_b32 s50, s50, 1
	s_add_u32 s49, s49, s50
	s_add_u32 s36, s6, s49
	s_addc_u32 s37, s7, 0
	s_lshl_b32 s50, s12, 13
	s_lshl_b32 s51, s14, 8
	s_add_u32 s50, s50, s51
	s_lshl_b32 s20, s25, 3
	s_waitcnt lgkmcnt(0)
	s_add_u32 s16, s16, s48
	s_addc_u32 s17, s17, 0
	s_add_u32 s26, s26, s50
	s_addc_u32 s27, s27, 0
	v_mad_u32_u24 v2, v9, s25, v14
	v_add_u32_e32 v3, s25, v2
	v_mad_u32_u24 v12, v13, s38, v11
	s_mov_b64 s[44:45], s[36:37]
	s_lshl_b32 s46, s38, 3
	s_cmp_eq_u32 s28, 0
	s_cbranch_scc1 .Lcv_l1_g1
	global_load_dwordx2 v[18:19], v4, s[26:27] offset:0
	global_load_dwordx2 v[20:21], v4, s[26:27] offset:32
	global_load_dwordx2 v[22:23], v4, s[26:27] offset:64
	global_load_dwordx2 v[24:25], v4, s[26:27] offset:96
	global_load_dwordx2 v[26:27], v4, s[26:27] offset:128
	global_load_dwordx2 v[28:29], v4, s[26:27] offset:160
	global_load_dwordx2 v[30:31], v4, s[26:27] offset:192
	global_load_dwordx2 v[32:33], v4, s[26:27] offset:224
	s_branch .Lcv_l1_gd
.Lcv_l1_g1:
	v_mov_b32_e32 v18, 1.0
	v_mov_b32_e32 v19, 1.0
	v_mov_b32_e32 v20, 1.0
	v_mov_b32_e32 v21, 1.0
	v_mov_b32_e32 v22, 1.0
	v_mov_b32_e32 v23, 1.0
	v_mov_b32_e32 v24, 1.0
	v_mov_b32_e32 v25, 1.0
	v_mov_b32_e32 v26, 1.0
	v_mov_b32_e32 v27, 1.0
	v_mov_b32_e32 v28, 1.0
	v_mov_b32_e32 v29, 1.0
	v_mov_b32_e32 v30, 1.0
	v_mov_b32_e32 v31, 1.0
	v_mov_b32_e32 v32, 1.0
	v_mov_b32_e32 v33, 1.0
.Lcv_l1_gd:
	global_load_dwordx4 v[100:103], v2, s[16:17]
	global_load_dwordx4 v[104:107], v3, s[16:17]
	s_add_u32 s16, s16, s20
	s_addc_u32 s17, s17, 0
	global_load_dwordx4 v[108:111], v2, s[16:17]
	global_load_dwordx4 v[112:115], v3, s[16:17]
	s_add_u32 s16, s16, s20
	s_addc_u32 s17, s17, 0
	global_load_dwordx4 v[116:119], v2, s[16:17]
	global_load_dwordx4 v[120:123], v3, s[16:17]
	s_add_u32 s16, s16, s20
	s_addc_u32 s17, s17, 0
	global_load_dwordx4 v[124:127], v2, s[16:17]
	global_load_dwordx4 v[128:131], v3, s[16:17]
	s_add_u32 s16, s16, s20
	s_addc_u32 s17, s17, 0
	global_load_dwordx4 v[132:135], v2, s[16:17]
	global_load_dwordx4 v[136:139], v3, s[16:17]
	s_add_u32 s16, s16, s20
	s_addc_u32 s17, s17, 0
	global_load_dwordx4 v[140:143], v2, s[16:17]
	global_load_dwordx4 v[144:147], v3, s[16:17]
	s_add_u32 s16, s16, s20
	s_addc_u32 s17, s17, 0
	global_load_dwordx4 v[148:151], v2, s[16:17]
	global_load_dwordx4 v[152:155], v3, s[16:17]
	s_add_u32 s16, s16, s20
	s_addc_u32 s17, s17, 0
	global_load_dwordx4 v[156:159], v2, s[16:17]
	global_load_dwordx4 v[160:163], v3, s[16:17]
	s_waitcnt vmcnt(16)
	s_branch .Lcv_PA
.Lcv_only1:
	s_waitcnt vmcnt(0)
	s_branch .Lcv_PA
.Lcv_WA:
	s_add_u32 s11, s8, s10
	s_cmp_ge_u32 s11, s9
	s_cbranch_scc1 .Lcv_WAlast
	s_waitcnt vmcnt(24)
	s_branch .Lcv_PA

.Lcv_PA:
	s_mov_b64 s[22:23], s[40:41]
	s_mov_b32 s24, s42
	v_mov_b32_e32 v17, v7
	v_pk_mul_f32 v[36:37], v[36:37], v[190:191] op_sel_hi:[1,0]
	v_pk_mul_f32 v[38:39], v[38:39], v[190:191] op_sel_hi:[1,0]
	v_pk_mul_f32 v[40:41], v[40:41], v[190:191] op_sel:[0,1] op_sel_hi:[1,1]
	v_pk_mul_f32 v[42:43], v[42:43], v[190:191] op_sel:[0,1] op_sel_hi:[1,1]
	v_cvt_pk_bf16_f32 v36, v36, v40
	v_cvt_pk_bf16_f32 v37, v37, v41
	v_cvt_pk_bf16_f32 v38, v38, v42
	v_cvt_pk_bf16_f32 v39, v39, v43
	ds_write_b64 v5, v[36:37] offset:0
	ds_write_b64 v5, v[38:39] offset:8
	v_pk_mul_f32 v[44:45], v[44:45], v[192:193] op_sel_hi:[1,0]
	v_pk_mul_f32 v[46:47], v[46:47], v[192:193] op_sel_hi:[1,0]
	v_pk_mul_f32 v[48:49], v[48:49], v[192:193] op_sel:[0,1] op_sel_hi:[1,1]
	v_pk_mul_f32 v[50:51], v[50:51], v[192:193] op_sel:[0,1] op_sel_hi:[1,1]
	v_cvt_pk_bf16_f32 v44, v44, v48
	v_cvt_pk_bf16_f32 v45, v45, v49
	v_cvt_pk_bf16_f32 v46, v46, v50
	v_cvt_pk_bf16_f32 v47, v47, v51
	ds_write_b64 v5, v[44:45] offset:1056
	ds_write_b64 v5, v[46:47] offset:1064
	v_pk_mul_f32 v[52:53], v[52:53], v[194:195] op_sel_hi:[1,0]
	v_pk_mul_f32 v[54:55], v[54:55], v[194:195] op_sel_hi:[1,0]
	v_pk_mul_f32 v[56:57], v[56:57], v[194:195] op_sel:[0,1] op_sel_hi:[1,1]
	v_pk_mul_f32 v[58:59], v[58:59], v[194:195] op_sel:[0,1] op_sel_hi:[1,1]
	v_cvt_pk_bf16_f32 v52, v52, v56
	v_cvt_pk_bf16_f32 v53, v53, v57
	v_cvt_pk_bf16_f32 v54, v54, v58
	v_cvt_pk_bf16_f32 v55, v55, v59
	ds_write_b64 v5, v[52:53] offset:2112
	ds_write_b64 v5, v[54:55] offset:2120
	v_pk_mul_f32 v[60:61], v[60:61], v[196:197] op_sel_hi:[1,0]
	v_pk_mul_f32 v[62:63], v[62:63], v[196:197] op_sel_hi:[1,0]
	v_pk_mul_f32 v[64:65], v[64:65], v[196:197] op_sel:[0,1] op_sel_hi:[1,1]
	v_pk_mul_f32 v[66:67], v[66:67], v[196:197] op_sel:[0,1] op_sel_hi:[1,1]
	v_cvt_pk_bf16_f32 v60, v60, v64
	v_cvt_pk_bf16_f32 v61, v61, v65
	v_cvt_pk_bf16_f32 v62, v62, v66
	v_cvt_pk_bf16_f32 v63, v63, v67
	ds_write_b64 v5, v[60:61] offset:3168
	ds_write_b64 v5, v[62:63] offset:3176
	v_pk_mul_f32 v[68:69], v[68:69], v[198:199] op_sel_hi:[1,0]
	v_pk_mul_f32 v[70:71], v[70:71], v[198:199] op_sel_hi:[1,0]
	v_pk_mul_f32 v[72:73], v[72:73], v[198:199] op_sel:[0,1] op_sel_hi:[1,1]
	v_pk_mul_f32 v[74:75], v[74:75], v[198:199] op_sel:[0,1] op_sel_hi:[1,1]
	v_cvt_pk_bf16_f32 v68, v68, v72
	v_cvt_pk_bf16_f32 v69, v69, v73
	v_cvt_pk_bf16_f32 v70, v70, v74
	v_cvt_pk_bf16_f32 v71, v71, v75
	ds_write_b64 v5, v[68:69] offset:4224
	ds_write_b64 v5, v[70:71] offset:4232
	v_pk_mul_f32 v[76:77], v[76:77], v[200:201] op_sel_hi:[1,0]
	v_pk_mul_f32 v[78:79], v[78:79], v[200:201] op_sel_hi:[1,0]
	v_pk_mul_f32 v[80:81], v[80:81], v[200:201] op_sel:[0,1] op_sel_hi:[1,1]
	v_pk_mul_f32 v[82:83], v[82:83], v[200:201] op_sel:[0,1] op_sel_hi:[1,1]
	v_cvt_pk_bf16_f32 v76, v76, v80
	v_cvt_pk_bf16_f32 v77, v77, v81
	v_cvt_pk_bf16_f32 v78, v78, v82
	v_cvt_pk_bf16_f32 v79, v79, v83
	ds_write_b64 v5, v[76:77] offset:5280
	ds_write_b64 v5, v[78:79] offset:5288
	v_pk_mul_f32 v[84:85], v[84:85], v[202:203] op_sel_hi:[1,0]
	v_pk_mul_f32 v[86:87], v[86:87], v[202:203] op_sel_hi:[1,0]
	v_pk_mul_f32 v[88:89], v[88:89], v[202:203] op_sel:[0,1] op_sel_hi:[1,1]
	v_pk_mul_f32 v[90:91], v[90:91], v[202:203] op_sel:[0,1] op_sel_hi:[1,1]
	v_cvt_pk_bf16_f32 v84, v84, v88
	v_cvt_pk_bf16_f32 v85, v85, v89
	v_cvt_pk_bf16_f32 v86, v86, v90
	v_cvt_pk_bf16_f32 v87, v87, v91
	ds_write_b64 v5, v[84:85] offset:6336
	ds_write_b64 v5, v[86:87] offset:6344
	v_pk_mul_f32 v[92:93], v[92:93], v[204:205] op_sel_hi:[1,0]
	v_pk_mul_f32 v[94:95], v[94:95], v[204:205] op_sel_hi:[1,0]
	v_pk_mul_f32 v[96:97], v[96:97], v[204:205] op_sel:[0,1] op_sel_hi:[1,1]
	v_pk_mul_f32 v[98:99], v[98:99], v[204:205] op_sel:[0,1] op_sel_hi:[1,1]
	v_cvt_pk_bf16_f32 v92, v92, v96
	v_cvt_pk_bf16_f32 v93, v93, v97
	v_cvt_pk_bf16_f32 v94, v94, v98
	v_cvt_pk_bf16_f32 v95, v95, v99
	ds_write_b64 v5, v[92:93] offset:7392
	ds_write_b64 v5, v[94:95] offset:7400
	s_waitcnt lgkmcnt(0)
	ds_read2_b32 v[214:215], v6 offset0:0 offset1:66
	ds_read2_b32 v[216:217], v6 offset0:132 offset1:198
	ds_read2_b32 v[218:219], v6 offset0:8 offset1:74
	ds_read2_b32 v[220:221], v6 offset0:140 offset1:206
	ds_read2_b32 v[222:223], v6 offset0:16 offset1:82
	ds_read2_b32 v[224:225], v6 offset0:148 offset1:214
	ds_read2_b32 v[226:227], v6 offset0:24 offset1:90
	ds_read2_b32 v[228:229], v6 offset0:156 offset1:222
	ds_read2_b32 v[230:231], v6 offset0:32 offset1:98
	ds_read2_b32 v[232:233], v6 offset0:164 offset1:230
	ds_read2_b32 v[234:235], v6 offset0:40 offset1:106
	ds_read2_b32 v[236:237], v6 offset0:172 offset1:238
	ds_read2_b32 v[238:239], v6 offset0:48 offset1:114
	ds_read2_b32 v[240:241], v6 offset0:180 offset1:246
	ds_read2_b32 v[242:243], v6 offset0:56 offset1:122
	ds_read2_b32 v[244:245], v6 offset0:188 offset1:254
	s_add_u32 s11, s8, s10
	s_add_u32 s11, s11, s10
	s_cmp_ge_u32 s11, s9
	s_cbranch_scc1 .Lcv_SA
	s_mov_b32 s12, 0
	s_mov_b32 s13, s11
	s_cmp_ge_u32 s13, 0x4180
	s_cbranch_scc0 .Lcv_d2A_l
	s_sub_u32 s13, s13, 0x4180
	s_add_u32 s12, s12, 1
	s_cmp_ge_u32 s13, 0x4180
	s_cbranch_scc0 .Lcv_d2A_l
	s_sub_u32 s13, s13, 0x4180
	s_add_u32 s12, s12, 1
	s_cmp_ge_u32 s13, 0x4180
	s_cbranch_scc0 .Lcv_d2A_l
	s_sub_u32 s13, s13, 0x4180
	s_add_u32 s12, s12, 1

.Lcv_l2A_gd:
	global_load_dwordx4 v[36:39], v2, s[16:17]
	global_load_dwordx4 v[40:43], v3, s[16:17]
	s_add_u32 s16, s16, s20
	s_addc_u32 s17, s17, 0
	global_load_dwordx4 v[44:47], v2, s[16:17]
	global_load_dwordx4 v[48:51], v3, s[16:17]
	s_add_u32 s16, s16, s20
	s_addc_u32 s17, s17, 0
	global_load_dwordx4 v[52:55], v2, s[16:17]
	global_load_dwordx4 v[56:59], v3, s[16:17]
	s_add_u32 s16, s16, s20
	s_addc_u32 s17, s17, 0
	global_load_dwordx4 v[60:63], v2, s[16:17]
	global_load_dwordx4 v[64:67], v3, s[16:17]
	s_add_u32 s16, s16, s20
	s_addc_u32 s17, s17, 0
	global_load_dwordx4 v[68:71], v2, s[16:17]
	global_load_dwordx4 v[72:75], v3, s[16:17]
	s_add_u32 s16, s16, s20
	s_addc_u32 s17, s17, 0
	global_load_dwordx4 v[76:79], v2, s[16:17]
	global_load_dwordx4 v[80:83], v3, s[16:17]
	s_add_u32 s16, s16, s20
	s_addc_u32 s17, s17, 0
	global_load_dwordx4 v[84:87], v2, s[16:17]
	global_load_dwordx4 v[88:91], v3, s[16:17]
	s_add_u32 s16, s16, s20
	s_addc_u32 s17, s17, 0
	global_load_dwordx4 v[92:95], v2, s[16:17]
	global_load_dwordx4 v[96:99], v3, s[16:17]
.Lcv_SA:
	s_waitcnt lgkmcnt(14)
	global_store_dwordx4 v17, v[214:217], s[22:23]
	s_add_u32 s22, s22, s24
	s_addc_u32 s23, s23, 0
	s_waitcnt lgkmcnt(12)
	global_store_dwordx4 v17, v[218:221], s[22:23]
	s_add_u32 s22, s22, s24
	s_addc_u32 s23, s23, 0
	s_waitcnt lgkmcnt(10)
	global_store_dwordx4 v17, v[222:225], s[22:23]
	s_add_u32 s22, s22, s24
	s_addc_u32 s23, s23, 0
	s_waitcnt lgkmcnt(8)
	global_store_dwordx4 v17, v[226:229], s[22:23]
	s_add_u32 s22, s22, s24
	s_addc_u32 s23, s23, 0
	s_waitcnt lgkmcnt(6)
	global_store_dwordx4 v17, v[230:233], s[22:23]
	s_add_u32 s22, s22, s24
	s_addc_u32 s23, s23, 0
	s_waitcnt lgkmcnt(4)
	global_store_dwordx4 v17, v[234:237], s[22:23]
	s_add_u32 s22, s22, s24
	s_addc_u32 s23, s23, 0
	s_waitcnt lgkmcnt(2)
	global_store_dwordx4 v17, v[238:241], s[22:23]
	s_add_u32 s22, s22, s24
	s_addc_u32 s23, s23, 0
	s_waitcnt lgkmcnt(0)
	global_store_dwordx4 v17, v[242:245], s[22:23]
	s_add_u32 s8, s8, s10
	s_cmp_ge_u32 s8, s9
	s_cbranch_scc1 .Lcv_exit

.Lcv_PB:
	s_mov_b64 s[22:23], s[44:45]
	s_mov_b32 s24, s46
	v_mov_b32_e32 v17, v12
	v_pk_mul_f32 v[100:101], v[100:101], v[18:19] op_sel_hi:[1,0]
	v_pk_mul_f32 v[102:103], v[102:103], v[18:19] op_sel_hi:[1,0]
	v_pk_mul_f32 v[104:105], v[104:105], v[18:19] op_sel:[0,1] op_sel_hi:[1,1]
	v_pk_mul_f32 v[106:107], v[106:107], v[18:19] op_sel:[0,1] op_sel_hi:[1,1]
	v_cvt_pk_bf16_f32 v100, v100, v104
	v_cvt_pk_bf16_f32 v101, v101, v105
	v_cvt_pk_bf16_f32 v102, v102, v106
	v_cvt_pk_bf16_f32 v103, v103, v107
	ds_write_b64 v5, v[100:101] offset:0
	ds_write_b64 v5, v[102:103] offset:8
	v_pk_mul_f32 v[108:109], v[108:109], v[20:21] op_sel_hi:[1,0]
	v_pk_mul_f32 v[110:111], v[110:111], v[20:21] op_sel_hi:[1,0]
	v_pk_mul_f32 v[112:113], v[112:113], v[20:21] op_sel:[0,1] op_sel_hi:[1,1]
	v_pk_mul_f32 v[114:115], v[114:115], v[20:21] op_sel:[0,1] op_sel_hi:[1,1]
	v_cvt_pk_bf16_f32 v108, v108, v112
	v_cvt_pk_bf16_f32 v109, v109, v113
	v_cvt_pk_bf16_f32 v110, v110, v114
	v_cvt_pk_bf16_f32 v111, v111, v115
	ds_write_b64 v5, v[108:109] offset:1056
	ds_write_b64 v5, v[110:111] offset:1064
	v_pk_mul_f32 v[116:117], v[116:117], v[22:23] op_sel_hi:[1,0]
	v_pk_mul_f32 v[118:119], v[118:119], v[22:23] op_sel_hi:[1,0]
	v_pk_mul_f32 v[120:121], v[120:121], v[22:23] op_sel:[0,1] op_sel_hi:[1,1]
	v_pk_mul_f32 v[122:123], v[122:123], v[22:23] op_sel:[0,1] op_sel_hi:[1,1]
	v_cvt_pk_bf16_f32 v116, v116, v120
	v_cvt_pk_bf16_f32 v117, v117, v121
	v_cvt_pk_bf16_f32 v118, v118, v122
	v_cvt_pk_bf16_f32 v119, v119, v123
	ds_write_b64 v5, v[116:117] offset:2112
	ds_write_b64 v5, v[118:119] offset:2120
	v_pk_mul_f32 v[124:125], v[124:125], v[24:25] op_sel_hi:[1,0]
	v_pk_mul_f32 v[126:127], v[126:127], v[24:25] op_sel_hi:[1,0]
	v_pk_mul_f32 v[128:129], v[128:129], v[24:25] op_sel:[0,1] op_sel_hi:[1,1]
	v_pk_mul_f32 v[130:131], v[130:131], v[24:25] op_sel:[0,1] op_sel_hi:[1,1]
	v_cvt_pk_bf16_f32 v124, v124, v128
	v_cvt_pk_bf16_f32 v125, v125, v129
	v_cvt_pk_bf16_f32 v126, v126, v130
	v_cvt_pk_bf16_f32 v127, v127, v131
	ds_write_b64 v5, v[124:125] offset:3168
	ds_write_b64 v5, v[126:127] offset:3176
	v_pk_mul_f32 v[132:133], v[132:133], v[26:27] op_sel_hi:[1,0]
	v_pk_mul_f32 v[134:135], v[134:135], v[26:27] op_sel_hi:[1,0]
	v_pk_mul_f32 v[136:137], v[136:137], v[26:27] op_sel:[0,1] op_sel_hi:[1,1]
	v_pk_mul_f32 v[138:139], v[138:139], v[26:27] op_sel:[0,1] op_sel_hi:[1,1]
	v_cvt_pk_bf16_f32 v132, v132, v136
	v_cvt_pk_bf16_f32 v133, v133, v137
	v_cvt_pk_bf16_f32 v134, v134, v138
	v_cvt_pk_bf16_f32 v135, v135, v139
	ds_write_b64 v5, v[132:133] offset:4224
	ds_write_b64 v5, v[134:135] offset:4232
	v_pk_mul_f32 v[140:141], v[140:141], v[28:29] op_sel_hi:[1,0]
	v_pk_mul_f32 v[142:143], v[142:143], v[28:29] op_sel_hi:[1,0]
	v_pk_mul_f32 v[144:145], v[144:145], v[28:29] op_sel:[0,1] op_sel_hi:[1,1]
	v_pk_mul_f32 v[146:147], v[146:147], v[28:29] op_sel:[0,1] op_sel_hi:[1,1]
	v_cvt_pk_bf16_f32 v140, v140, v144
	v_cvt_pk_bf16_f32 v141, v141, v145
	v_cvt_pk_bf16_f32 v142, v142, v146
	v_cvt_pk_bf16_f32 v143, v143, v147
	ds_write_b64 v5, v[140:141] offset:5280
	ds_write_b64 v5, v[142:143] offset:5288
	v_pk_mul_f32 v[148:149], v[148:149], v[30:31] op_sel_hi:[1,0]
	v_pk_mul_f32 v[150:151], v[150:151], v[30:31] op_sel_hi:[1,0]
	v_pk_mul_f32 v[152:153], v[152:153], v[30:31] op_sel:[0,1] op_sel_hi:[1,1]
	v_pk_mul_f32 v[154:155], v[154:155], v[30:31] op_sel:[0,1] op_sel_hi:[1,1]
	v_cvt_pk_bf16_f32 v148, v148, v152
	v_cvt_pk_bf16_f32 v149, v149, v153
	v_cvt_pk_bf16_f32 v150, v150, v154
	v_cvt_pk_bf16_f32 v151, v151, v155
	ds_write_b64 v5, v[148:149] offset:6336
	ds_write_b64 v5, v[150:151] offset:6344
	v_pk_mul_f32 v[156:157], v[156:157], v[32:33] op_sel_hi:[1,0]
	v_pk_mul_f32 v[158:159], v[158:159], v[32:33] op_sel_hi:[1,0]
	v_pk_mul_f32 v[160:161], v[160:161], v[32:33] op_sel:[0,1] op_sel_hi:[1,1]
	v_pk_mul_f32 v[162:163], v[162:163], v[32:33] op_sel:[0,1] op_sel_hi:[1,1]
	v_cvt_pk_bf16_f32 v156, v156, v160
	v_cvt_pk_bf16_f32 v157, v157, v161
	v_cvt_pk_bf16_f32 v158, v158, v162
	v_cvt_pk_bf16_f32 v159, v159, v163
	ds_write_b64 v5, v[156:157] offset:7392
	ds_write_b64 v5, v[158:159] offset:7400
	s_waitcnt lgkmcnt(0)
	ds_read2_b32 v[214:215], v6 offset0:0 offset1:66
	ds_read2_b32 v[216:217], v6 offset0:132 offset1:198
	ds_read2_b32 v[218:219], v6 offset0:8 offset1:74
	ds_read2_b32 v[220:221], v6 offset0:140 offset1:206
	ds_read2_b32 v[222:223], v6 offset0:16 offset1:82
	ds_read2_b32 v[224:225], v6 offset0:148 offset1:214
	ds_read2_b32 v[226:227], v6 offset0:24 offset1:90
	ds_read2_b32 v[228:229], v6 offset0:156 offset1:222
	ds_read2_b32 v[230:231], v6 offset0:32 offset1:98
	ds_read2_b32 v[232:233], v6 offset0:164 offset1:230
	ds_read2_b32 v[234:235], v6 offset0:40 offset1:106
	ds_read2_b32 v[236:237], v6 offset0:172 offset1:238
	ds_read2_b32 v[238:239], v6 offset0:48 offset1:114
	ds_read2_b32 v[240:241], v6 offset0:180 offset1:246
	ds_read2_b32 v[242:243], v6 offset0:56 offset1:122
	ds_read2_b32 v[244:245], v6 offset0:188 offset1:254
	s_add_u32 s11, s8, s10
	s_add_u32 s11, s11, s10
	s_cmp_ge_u32 s11, s9
	s_cbranch_scc1 .Lcv_SB
	s_mov_b32 s12, 0
	s_mov_b32 s13, s11
	s_cmp_ge_u32 s13, 0x4180
	s_cbranch_scc0 .Lcv_d2B_l
	s_sub_u32 s13, s13, 0x4180
	s_add_u32 s12, s12, 1
	s_cmp_ge_u32 s13, 0x4180
	s_cbranch_scc0 .Lcv_d2B_l
	s_sub_u32 s13, s13, 0x4180
	s_add_u32 s12, s12, 1
	s_cmp_ge_u32 s13, 0x4180
	s_cbranch_scc0 .Lcv_d2B_l
	s_sub_u32 s13, s13, 0x4180
	s_add_u32 s12, s12, 1

.Lcv_l2B_gd:
	global_load_dwordx4 v[100:103], v2, s[16:17]
	global_load_dwordx4 v[104:107], v3, s[16:17]
	s_add_u32 s16, s16, s20
	s_addc_u32 s17, s17, 0
	global_load_dwordx4 v[108:111], v2, s[16:17]
	global_load_dwordx4 v[112:115], v3, s[16:17]
	s_add_u32 s16, s16, s20
	s_addc_u32 s17, s17, 0
	global_load_dwordx4 v[116:119], v2, s[16:17]
	global_load_dwordx4 v[120:123], v3, s[16:17]
	s_add_u32 s16, s16, s20
	s_addc_u32 s17, s17, 0
	global_load_dwordx4 v[124:127], v2, s[16:17]
	global_load_dwordx4 v[128:131], v3, s[16:17]
	s_add_u32 s16, s16, s20
	s_addc_u32 s17, s17, 0
	global_load_dwordx4 v[132:135], v2, s[16:17]
	global_load_dwordx4 v[136:139], v3, s[16:17]
	s_add_u32 s16, s16, s20
	s_addc_u32 s17, s17, 0
	global_load_dwordx4 v[140:143], v2, s[16:17]
	global_load_dwordx4 v[144:147], v3, s[16:17]
	s_add_u32 s16, s16, s20
	s_addc_u32 s17, s17, 0
	global_load_dwordx4 v[148:151], v2, s[16:17]
	global_load_dwordx4 v[152:155], v3, s[16:17]
	s_add_u32 s16, s16, s20
	s_addc_u32 s17, s17, 0
	global_load_dwordx4 v[156:159], v2, s[16:17]
	global_load_dwordx4 v[160:163], v3, s[16:17]
.Lcv_SB:
	s_waitcnt lgkmcnt(14)
	global_store_dwordx4 v17, v[214:217], s[22:23]
	s_add_u32 s22, s22, s24
	s_addc_u32 s23, s23, 0
	s_waitcnt lgkmcnt(12)
	global_store_dwordx4 v17, v[218:221], s[22:23]
	s_add_u32 s22, s22, s24
	s_addc_u32 s23, s23, 0
	s_waitcnt lgkmcnt(10)
	global_store_dwordx4 v17, v[222:225], s[22:23]
	s_add_u32 s22, s22, s24
	s_addc_u32 s23, s23, 0
	s_waitcnt lgkmcnt(8)
	global_store_dwordx4 v17, v[226:229], s[22:23]
	s_add_u32 s22, s22, s24
	s_addc_u32 s23, s23, 0
	s_waitcnt lgkmcnt(6)
	global_store_dwordx4 v17, v[230:233], s[22:23]
	s_add_u32 s22, s22, s24
	s_addc_u32 s23, s23, 0
	s_waitcnt lgkmcnt(4)
	global_store_dwordx4 v17, v[234:237], s[22:23]
	s_add_u32 s22, s22, s24
	s_addc_u32 s23, s23, 0
	s_waitcnt lgkmcnt(2)
	global_store_dwordx4 v17, v[238:241], s[22:23]
	s_add_u32 s22, s22, s24
	s_addc_u32 s23, s23, 0
	s_waitcnt lgkmcnt(0)
	global_store_dwordx4 v17, v[242:245], s[22:23]
	s_add_u32 s8, s8, s10
	s_cmp_ge_u32 s8, s9
	s_cbranch_scc1 .Lcv_exit
	s_branch .Lcv_WA
.Lcv_shallow:
	s_mov_b32 s11, s8
	s_mov_b32 s12, 0
	s_mov_b32 s13, s11
	s_cmp_ge_u32 s13, 0x4180
	s_cbranch_scc0 .Lcv_sd0_l
	s_sub_u32 s13, s13, 0x4180
	s_add_u32 s12, s12, 1
	s_cmp_ge_u32 s13, 0x4180
	s_cbranch_scc0 .Lcv_sd0_l
	s_sub_u32 s13, s13, 0x4180
	s_add_u32 s12, s12, 1
	s_cmp_ge_u32 s13, 0x4180
	s_cbranch_scc0 .Lcv_sd0_l
	s_sub_u32 s13, s13, 0x4180
	s_add_u32 s12, s12, 1

.Lcv_sloop:
	s_add_u32 s11, s8, s10
	s_cmp_ge_u32 s11, s9
	s_cbranch_scc1 .Lcv_slastA
	s_mov_b32 s12, 0
	s_mov_b32 s13, s11
	s_cmp_ge_u32 s13, 0x4180
	s_cbranch_scc0 .Lcv_sd1_l
	s_sub_u32 s13, s13, 0x4180
	s_add_u32 s12, s12, 1
	s_cmp_ge_u32 s13, 0x4180
	s_cbranch_scc0 .Lcv_sd1_l
	s_sub_u32 s13, s13, 0x4180
	s_add_u32 s12, s12, 1
	s_cmp_ge_u32 s13, 0x4180
	s_cbranch_scc0 .Lcv_sd1_l
	s_sub_u32 s13, s13, 0x4180
	s_add_u32 s12, s12, 1

.Lcv_sl1_gd:
	global_load_dwordx4 v[100:103], v2, s[16:17]
	global_load_dwordx4 v[104:107], v3, s[16:17]
	s_add_u32 s16, s16, s20
	s_addc_u32 s17, s17, 0
	global_load_dwordx4 v[108:111], v2, s[16:17]
	global_load_dwordx4 v[112:115], v3, s[16:17]
	s_add_u32 s16, s16, s20
	s_addc_u32 s17, s17, 0
	global_load_dwordx4 v[116:119], v2, s[16:17]
	global_load_dwordx4 v[120:123], v3, s[16:17]
	s_add_u32 s16, s16, s20
	s_addc_u32 s17, s17, 0
	global_load_dwordx4 v[124:127], v2, s[16:17]
	global_load_dwordx4 v[128:131], v3, s[16:17]
	s_add_u32 s16, s16, s20
	s_addc_u32 s17, s17, 0
	global_load_dwordx4 v[132:135], v2, s[16:17]
	global_load_dwordx4 v[136:139], v3, s[16:17]
	s_add_u32 s16, s16, s20
	s_addc_u32 s17, s17, 0
	global_load_dwordx4 v[140:143], v2, s[16:17]
	global_load_dwordx4 v[144:147], v3, s[16:17]
	s_add_u32 s16, s16, s20
	s_addc_u32 s17, s17, 0
	global_load_dwordx4 v[148:151], v2, s[16:17]
	global_load_dwordx4 v[152:155], v3, s[16:17]
	s_add_u32 s16, s16, s20
	s_addc_u32 s17, s17, 0
	global_load_dwordx4 v[156:159], v2, s[16:17]
	global_load_dwordx4 v[160:163], v3, s[16:17]
	s_waitcnt vmcnt(16)
	v_pk_mul_f32 v[36:37], v[36:37], v[190:191] op_sel_hi:[1,0]
	v_pk_mul_f32 v[38:39], v[38:39], v[190:191] op_sel_hi:[1,0]
	v_pk_mul_f32 v[40:41], v[40:41], v[190:191] op_sel:[0,1] op_sel_hi:[1,1]
	v_pk_mul_f32 v[42:43], v[42:43], v[190:191] op_sel:[0,1] op_sel_hi:[1,1]
	v_cvt_pk_bf16_f32 v36, v36, v40
	v_cvt_pk_bf16_f32 v37, v37, v41
	v_cvt_pk_bf16_f32 v38, v38, v42
	v_cvt_pk_bf16_f32 v39, v39, v43
	ds_write_b64 v5, v[36:37] offset:0
	ds_write_b64 v5, v[38:39] offset:8
	v_pk_mul_f32 v[44:45], v[44:45], v[192:193] op_sel_hi:[1,0]
	v_pk_mul_f32 v[46:47], v[46:47], v[192:193] op_sel_hi:[1,0]
	v_pk_mul_f32 v[48:49], v[48:49], v[192:193] op_sel:[0,1] op_sel_hi:[1,1]
	v_pk_mul_f32 v[50:51], v[50:51], v[192:193] op_sel:[0,1] op_sel_hi:[1,1]
	v_cvt_pk_bf16_f32 v44, v44, v48
	v_cvt_pk_bf16_f32 v45, v45, v49
	v_cvt_pk_bf16_f32 v46, v46, v50
	v_cvt_pk_bf16_f32 v47, v47, v51
	ds_write_b64 v5, v[44:45] offset:1056
	ds_write_b64 v5, v[46:47] offset:1064
	v_pk_mul_f32 v[52:53], v[52:53], v[194:195] op_sel_hi:[1,0]
	v_pk_mul_f32 v[54:55], v[54:55], v[194:195] op_sel_hi:[1,0]
	v_pk_mul_f32 v[56:57], v[56:57], v[194:195] op_sel:[0,1] op_sel_hi:[1,1]
	v_pk_mul_f32 v[58:59], v[58:59], v[194:195] op_sel:[0,1] op_sel_hi:[1,1]
	v_cvt_pk_bf16_f32 v52, v52, v56
	v_cvt_pk_bf16_f32 v53, v53, v57
	v_cvt_pk_bf16_f32 v54, v54, v58
	v_cvt_pk_bf16_f32 v55, v55, v59
	ds_write_b64 v5, v[52:53] offset:2112
	ds_write_b64 v5, v[54:55] offset:2120
	v_pk_mul_f32 v[60:61], v[60:61], v[196:197] op_sel_hi:[1,0]
	v_pk_mul_f32 v[62:63], v[62:63], v[196:197] op_sel_hi:[1,0]
	v_pk_mul_f32 v[64:65], v[64:65], v[196:197] op_sel:[0,1] op_sel_hi:[1,1]
	v_pk_mul_f32 v[66:67], v[66:67], v[196:197] op_sel:[0,1] op_sel_hi:[1,1]
	v_cvt_pk_bf16_f32 v60, v60, v64
	v_cvt_pk_bf16_f32 v61, v61, v65
	v_cvt_pk_bf16_f32 v62, v62, v66
	v_cvt_pk_bf16_f32 v63, v63, v67
	ds_write_b64 v5, v[60:61] offset:3168
	ds_write_b64 v5, v[62:63] offset:3176
	v_pk_mul_f32 v[68:69], v[68:69], v[198:199] op_sel_hi:[1,0]
	v_pk_mul_f32 v[70:71], v[70:71], v[198:199] op_sel_hi:[1,0]
	v_pk_mul_f32 v[72:73], v[72:73], v[198:199] op_sel:[0,1] op_sel_hi:[1,1]
	v_pk_mul_f32 v[74:75], v[74:75], v[198:199] op_sel:[0,1] op_sel_hi:[1,1]
	v_cvt_pk_bf16_f32 v68, v68, v72
	v_cvt_pk_bf16_f32 v69, v69, v73
	v_cvt_pk_bf16_f32 v70, v70, v74
	v_cvt_pk_bf16_f32 v71, v71, v75
	ds_write_b64 v5, v[68:69] offset:4224
	ds_write_b64 v5, v[70:71] offset:4232
	v_pk_mul_f32 v[76:77], v[76:77], v[200:201] op_sel_hi:[1,0]
	v_pk_mul_f32 v[78:79], v[78:79], v[200:201] op_sel_hi:[1,0]
	v_pk_mul_f32 v[80:81], v[80:81], v[200:201] op_sel:[0,1] op_sel_hi:[1,1]
	v_pk_mul_f32 v[82:83], v[82:83], v[200:201] op_sel:[0,1] op_sel_hi:[1,1]
	v_cvt_pk_bf16_f32 v76, v76, v80
	v_cvt_pk_bf16_f32 v77, v77, v81
	v_cvt_pk_bf16_f32 v78, v78, v82
	v_cvt_pk_bf16_f32 v79, v79, v83
	ds_write_b64 v5, v[76:77] offset:5280
	ds_write_b64 v5, v[78:79] offset:5288
	v_pk_mul_f32 v[84:85], v[84:85], v[202:203] op_sel_hi:[1,0]
	v_pk_mul_f32 v[86:87], v[86:87], v[202:203] op_sel_hi:[1,0]
	v_pk_mul_f32 v[88:89], v[88:89], v[202:203] op_sel:[0,1] op_sel_hi:[1,1]
	v_pk_mul_f32 v[90:91], v[90:91], v[202:203] op_sel:[0,1] op_sel_hi:[1,1]
	v_cvt_pk_bf16_f32 v84, v84, v88
	v_cvt_pk_bf16_f32 v85, v85, v89
	v_cvt_pk_bf16_f32 v86, v86, v90
	v_cvt_pk_bf16_f32 v87, v87, v91
	ds_write_b64 v5, v[84:85] offset:6336
	ds_write_b64 v5, v[86:87] offset:6344
	v_pk_mul_f32 v[92:93], v[92:93], v[204:205] op_sel_hi:[1,0]
	v_pk_mul_f32 v[94:95], v[94:95], v[204:205] op_sel_hi:[1,0]
	v_pk_mul_f32 v[96:97], v[96:97], v[204:205] op_sel:[0,1] op_sel_hi:[1,1]
	v_pk_mul_f32 v[98:99], v[98:99], v[204:205] op_sel:[0,1] op_sel_hi:[1,1]
	v_cvt_pk_bf16_f32 v92, v92, v96
	v_cvt_pk_bf16_f32 v93, v93, v97
	v_cvt_pk_bf16_f32 v94, v94, v98
	v_cvt_pk_bf16_f32 v95, v95, v99
	ds_write_b64 v5, v[92:93] offset:7392
	ds_write_b64 v5, v[94:95] offset:7400
	s_waitcnt lgkmcnt(0)
	ds_read2_b32 v[214:215], v6 offset0:0 offset1:66
	ds_read2_b32 v[216:217], v6 offset0:132 offset1:198
	ds_read2_b32 v[218:219], v6 offset0:8 offset1:74
	ds_read2_b32 v[220:221], v6 offset0:140 offset1:206
	ds_read2_b32 v[222:223], v6 offset0:16 offset1:82
	ds_read2_b32 v[224:225], v6 offset0:148 offset1:214
	ds_read2_b32 v[226:227], v6 offset0:24 offset1:90
	ds_read2_b32 v[228:229], v6 offset0:156 offset1:222
	ds_read2_b32 v[230:231], v6 offset0:32 offset1:98
	ds_read2_b32 v[232:233], v6 offset0:164 offset1:230
	ds_read2_b32 v[234:235], v6 offset0:40 offset1:106
	ds_read2_b32 v[236:237], v6 offset0:172 offset1:238
	ds_read2_b32 v[238:239], v6 offset0:48 offset1:114
	ds_read2_b32 v[240:241], v6 offset0:180 offset1:246
	ds_read2_b32 v[242:243], v6 offset0:56 offset1:122
	ds_read2_b32 v[244:245], v6 offset0:188 offset1:254
	s_waitcnt lgkmcnt(14)
	global_store_dwordx4 v7, v[214:217], s[40:41]
	s_add_u32 s40, s40, s42
	s_addc_u32 s41, s41, 0
	s_waitcnt lgkmcnt(12)
	global_store_dwordx4 v7, v[218:221], s[40:41]
	s_add_u32 s40, s40, s42
	s_addc_u32 s41, s41, 0
	s_waitcnt lgkmcnt(10)
	global_store_dwordx4 v7, v[222:225], s[40:41]
	s_add_u32 s40, s40, s42
	s_addc_u32 s41, s41, 0
	s_waitcnt lgkmcnt(8)
	global_store_dwordx4 v7, v[226:229], s[40:41]
	s_add_u32 s40, s40, s42
	s_addc_u32 s41, s41, 0
	s_waitcnt lgkmcnt(6)
	global_store_dwordx4 v7, v[230:233], s[40:41]
	s_add_u32 s40, s40, s42
	s_addc_u32 s41, s41, 0
	s_waitcnt lgkmcnt(4)
	global_store_dwordx4 v7, v[234:237], s[40:41]
	s_add_u32 s40, s40, s42
	s_addc_u32 s41, s41, 0
	s_waitcnt lgkmcnt(2)
	global_store_dwordx4 v7, v[238:241], s[40:41]
	s_add_u32 s40, s40, s42
	s_addc_u32 s41, s41, 0
	s_waitcnt lgkmcnt(0)
	global_store_dwordx4 v7, v[242:245], s[40:41]
	s_mov_b32 s8, s11
	s_add_u32 s11, s8, s10
	s_cmp_ge_u32 s11, s9
	s_cbranch_scc1 .Lcv_slastB
	s_mov_b32 s12, 0
	s_mov_b32 s13, s11
	s_cmp_ge_u32 s13, 0x4180
	s_cbranch_scc0 .Lcv_sd2_l
	s_sub_u32 s13, s13, 0x4180
	s_add_u32 s12, s12, 1
	s_cmp_ge_u32 s13, 0x4180
	s_cbranch_scc0 .Lcv_sd2_l
	s_sub_u32 s13, s13, 0x4180
	s_add_u32 s12, s12, 1
	s_cmp_ge_u32 s13, 0x4180
	s_cbranch_scc0 .Lcv_sd2_l
	s_sub_u32 s13, s13, 0x4180
	s_add_u32 s12, s12, 1

.Lcv_sl2_gd:
	global_load_dwordx4 v[36:39], v2, s[16:17]
	global_load_dwordx4 v[40:43], v3, s[16:17]
	s_add_u32 s16, s16, s20
	s_addc_u32 s17, s17, 0
	global_load_dwordx4 v[44:47], v2, s[16:17]
	global_load_dwordx4 v[48:51], v3, s[16:17]
	s_add_u32 s16, s16, s20
	s_addc_u32 s17, s17, 0
	global_load_dwordx4 v[52:55], v2, s[16:17]
	global_load_dwordx4 v[56:59], v3, s[16:17]
	s_add_u32 s16, s16, s20
	s_addc_u32 s17, s17, 0
	global_load_dwordx4 v[60:63], v2, s[16:17]
	global_load_dwordx4 v[64:67], v3, s[16:17]
	s_add_u32 s16, s16, s20
	s_addc_u32 s17, s17, 0
	global_load_dwordx4 v[68:71], v2, s[16:17]
	global_load_dwordx4 v[72:75], v3, s[16:17]
	s_add_u32 s16, s16, s20
	s_addc_u32 s17, s17, 0
	global_load_dwordx4 v[76:79], v2, s[16:17]
	global_load_dwordx4 v[80:83], v3, s[16:17]
	s_add_u32 s16, s16, s20
	s_addc_u32 s17, s17, 0
	global_load_dwordx4 v[84:87], v2, s[16:17]
	global_load_dwordx4 v[88:91], v3, s[16:17]
	s_add_u32 s16, s16, s20
	s_addc_u32 s17, s17, 0
	global_load_dwordx4 v[92:95], v2, s[16:17]
	global_load_dwordx4 v[96:99], v3, s[16:17]
	s_waitcnt vmcnt(16)
	v_pk_mul_f32 v[100:101], v[100:101], v[18:19] op_sel_hi:[1,0]
	v_pk_mul_f32 v[102:103], v[102:103], v[18:19] op_sel_hi:[1,0]
	v_pk_mul_f32 v[104:105], v[104:105], v[18:19] op_sel:[0,1] op_sel_hi:[1,1]
	v_pk_mul_f32 v[106:107], v[106:107], v[18:19] op_sel:[0,1] op_sel_hi:[1,1]
	v_cvt_pk_bf16_f32 v100, v100, v104
	v_cvt_pk_bf16_f32 v101, v101, v105
	v_cvt_pk_bf16_f32 v102, v102, v106
	v_cvt_pk_bf16_f32 v103, v103, v107
	ds_write_b64 v5, v[100:101] offset:0
	ds_write_b64 v5, v[102:103] offset:8
	v_pk_mul_f32 v[108:109], v[108:109], v[20:21] op_sel_hi:[1,0]
	v_pk_mul_f32 v[110:111], v[110:111], v[20:21] op_sel_hi:[1,0]
	v_pk_mul_f32 v[112:113], v[112:113], v[20:21] op_sel:[0,1] op_sel_hi:[1,1]
	v_pk_mul_f32 v[114:115], v[114:115], v[20:21] op_sel:[0,1] op_sel_hi:[1,1]
	v_cvt_pk_bf16_f32 v108, v108, v112
	v_cvt_pk_bf16_f32 v109, v109, v113
	v_cvt_pk_bf16_f32 v110, v110, v114
	v_cvt_pk_bf16_f32 v111, v111, v115
	ds_write_b64 v5, v[108:109] offset:1056
	ds_write_b64 v5, v[110:111] offset:1064
	v_pk_mul_f32 v[116:117], v[116:117], v[22:23] op_sel_hi:[1,0]
	v_pk_mul_f32 v[118:119], v[118:119], v[22:23] op_sel_hi:[1,0]
	v_pk_mul_f32 v[120:121], v[120:121], v[22:23] op_sel:[0,1] op_sel_hi:[1,1]
	v_pk_mul_f32 v[122:123], v[122:123], v[22:23] op_sel:[0,1] op_sel_hi:[1,1]
	v_cvt_pk_bf16_f32 v116, v116, v120
	v_cvt_pk_bf16_f32 v117, v117, v121
	v_cvt_pk_bf16_f32 v118, v118, v122
	v_cvt_pk_bf16_f32 v119, v119, v123
	ds_write_b64 v5, v[116:117] offset:2112
	ds_write_b64 v5, v[118:119] offset:2120
	v_pk_mul_f32 v[124:125], v[124:125], v[24:25] op_sel_hi:[1,0]
	v_pk_mul_f32 v[126:127], v[126:127], v[24:25] op_sel_hi:[1,0]
	v_pk_mul_f32 v[128:129], v[128:129], v[24:25] op_sel:[0,1] op_sel_hi:[1,1]
	v_pk_mul_f32 v[130:131], v[130:131], v[24:25] op_sel:[0,1] op_sel_hi:[1,1]
	v_cvt_pk_bf16_f32 v124, v124, v128
	v_cvt_pk_bf16_f32 v125, v125, v129
	v_cvt_pk_bf16_f32 v126, v126, v130
	v_cvt_pk_bf16_f32 v127, v127, v131
	ds_write_b64 v5, v[124:125] offset:3168
	ds_write_b64 v5, v[126:127] offset:3176
	v_pk_mul_f32 v[132:133], v[132:133], v[26:27] op_sel_hi:[1,0]
	v_pk_mul_f32 v[134:135], v[134:135], v[26:27] op_sel_hi:[1,0]
	v_pk_mul_f32 v[136:137], v[136:137], v[26:27] op_sel:[0,1] op_sel_hi:[1,1]
	v_pk_mul_f32 v[138:139], v[138:139], v[26:27] op_sel:[0,1] op_sel_hi:[1,1]
	v_cvt_pk_bf16_f32 v132, v132, v136
	v_cvt_pk_bf16_f32 v133, v133, v137
	v_cvt_pk_bf16_f32 v134, v134, v138
	v_cvt_pk_bf16_f32 v135, v135, v139
	ds_write_b64 v5, v[132:133] offset:4224
	ds_write_b64 v5, v[134:135] offset:4232
	v_pk_mul_f32 v[140:141], v[140:141], v[28:29] op_sel_hi:[1,0]
	v_pk_mul_f32 v[142:143], v[142:143], v[28:29] op_sel_hi:[1,0]
	v_pk_mul_f32 v[144:145], v[144:145], v[28:29] op_sel:[0,1] op_sel_hi:[1,1]
	v_pk_mul_f32 v[146:147], v[146:147], v[28:29] op_sel:[0,1] op_sel_hi:[1,1]
	v_cvt_pk_bf16_f32 v140, v140, v144
	v_cvt_pk_bf16_f32 v141, v141, v145
	v_cvt_pk_bf16_f32 v142, v142, v146
	v_cvt_pk_bf16_f32 v143, v143, v147
	ds_write_b64 v5, v[140:141] offset:5280
	ds_write_b64 v5, v[142:143] offset:5288
	v_pk_mul_f32 v[148:149], v[148:149], v[30:31] op_sel_hi:[1,0]
	v_pk_mul_f32 v[150:151], v[150:151], v[30:31] op_sel_hi:[1,0]
	v_pk_mul_f32 v[152:153], v[152:153], v[30:31] op_sel:[0,1] op_sel_hi:[1,1]
	v_pk_mul_f32 v[154:155], v[154:155], v[30:31] op_sel:[0,1] op_sel_hi:[1,1]
	v_cvt_pk_bf16_f32 v148, v148, v152
	v_cvt_pk_bf16_f32 v149, v149, v153
	v_cvt_pk_bf16_f32 v150, v150, v154
	v_cvt_pk_bf16_f32 v151, v151, v155
	ds_write_b64 v5, v[148:149] offset:6336
	ds_write_b64 v5, v[150:151] offset:6344
	v_pk_mul_f32 v[156:157], v[156:157], v[32:33] op_sel_hi:[1,0]
	v_pk_mul_f32 v[158:159], v[158:159], v[32:33] op_sel_hi:[1,0]
	v_pk_mul_f32 v[160:161], v[160:161], v[32:33] op_sel:[0,1] op_sel_hi:[1,1]
	v_pk_mul_f32 v[162:163], v[162:163], v[32:33] op_sel:[0,1] op_sel_hi:[1,1]
	v_cvt_pk_bf16_f32 v156, v156, v160
	v_cvt_pk_bf16_f32 v157, v157, v161
	v_cvt_pk_bf16_f32 v158, v158, v162
	v_cvt_pk_bf16_f32 v159, v159, v163
	ds_write_b64 v5, v[156:157] offset:7392
	ds_write_b64 v5, v[158:159] offset:7400
	s_waitcnt lgkmcnt(0)
	ds_read2_b32 v[214:215], v6 offset0:0 offset1:66
	ds_read2_b32 v[216:217], v6 offset0:132 offset1:198
	ds_read2_b32 v[218:219], v6 offset0:8 offset1:74
	ds_read2_b32 v[220:221], v6 offset0:140 offset1:206
	ds_read2_b32 v[222:223], v6 offset0:16 offset1:82
	ds_read2_b32 v[224:225], v6 offset0:148 offset1:214
	ds_read2_b32 v[226:227], v6 offset0:24 offset1:90
	ds_read2_b32 v[228:229], v6 offset0:156 offset1:222
	ds_read2_b32 v[230:231], v6 offset0:32 offset1:98
	ds_read2_b32 v[232:233], v6 offset0:164 offset1:230
	ds_read2_b32 v[234:235], v6 offset0:40 offset1:106
	ds_read2_b32 v[236:237], v6 offset0:172 offset1:238
	ds_read2_b32 v[238:239], v6 offset0:48 offset1:114
	ds_read2_b32 v[240:241], v6 offset0:180 offset1:246
	ds_read2_b32 v[242:243], v6 offset0:56 offset1:122
	ds_read2_b32 v[244:245], v6 offset0:188 offset1:254
	s_waitcnt lgkmcnt(14)
	global_store_dwordx4 v12, v[214:217], s[44:45]
	s_add_u32 s44, s44, s46
	s_addc_u32 s45, s45, 0
	s_waitcnt lgkmcnt(12)
	global_store_dwordx4 v12, v[218:221], s[44:45]
	s_add_u32 s44, s44, s46
	s_addc_u32 s45, s45, 0
	s_waitcnt lgkmcnt(10)
	global_store_dwordx4 v12, v[222:225], s[44:45]
	s_add_u32 s44, s44, s46
	s_addc_u32 s45, s45, 0
	s_waitcnt lgkmcnt(8)
	global_store_dwordx4 v12, v[226:229], s[44:45]
	s_add_u32 s44, s44, s46
	s_addc_u32 s45, s45, 0
	s_waitcnt lgkmcnt(6)
	global_store_dwordx4 v12, v[230:233], s[44:45]
	s_add_u32 s44, s44, s46
	s_addc_u32 s45, s45, 0
	s_waitcnt lgkmcnt(4)
	global_store_dwordx4 v12, v[234:237], s[44:45]
	s_add_u32 s44, s44, s46
	s_addc_u32 s45, s45, 0
	s_waitcnt lgkmcnt(2)
	global_store_dwordx4 v12, v[238:241], s[44:45]
	s_add_u32 s44, s44, s46
	s_addc_u32 s45, s45, 0
	s_waitcnt lgkmcnt(0)
	global_store_dwordx4 v12, v[242:245], s[44:45]
	s_mov_b32 s8, s11
	s_branch .Lcv_sloop
.Lcv_slastA:
	s_waitcnt vmcnt(0)
	v_pk_mul_f32 v[36:37], v[36:37], v[190:191] op_sel_hi:[1,0]
	v_pk_mul_f32 v[38:39], v[38:39], v[190:191] op_sel_hi:[1,0]
	v_pk_mul_f32 v[40:41], v[40:41], v[190:191] op_sel:[0,1] op_sel_hi:[1,1]
	v_pk_mul_f32 v[42:43], v[42:43], v[190:191] op_sel:[0,1] op_sel_hi:[1,1]
	v_cvt_pk_bf16_f32 v36, v36, v40
	v_cvt_pk_bf16_f32 v37, v37, v41
	v_cvt_pk_bf16_f32 v38, v38, v42
	v_cvt_pk_bf16_f32 v39, v39, v43
	ds_write_b64 v5, v[36:37] offset:0
	ds_write_b64 v5, v[38:39] offset:8
	v_pk_mul_f32 v[44:45], v[44:45], v[192:193] op_sel_hi:[1,0]
	v_pk_mul_f32 v[46:47], v[46:47], v[192:193] op_sel_hi:[1,0]
	v_pk_mul_f32 v[48:49], v[48:49], v[192:193] op_sel:[0,1] op_sel_hi:[1,1]
	v_pk_mul_f32 v[50:51], v[50:51], v[192:193] op_sel:[0,1] op_sel_hi:[1,1]
	v_cvt_pk_bf16_f32 v44, v44, v48
	v_cvt_pk_bf16_f32 v45, v45, v49
	v_cvt_pk_bf16_f32 v46, v46, v50
	v_cvt_pk_bf16_f32 v47, v47, v51
	ds_write_b64 v5, v[44:45] offset:1056
	ds_write_b64 v5, v[46:47] offset:1064
	v_pk_mul_f32 v[52:53], v[52:53], v[194:195] op_sel_hi:[1,0]
	v_pk_mul_f32 v[54:55], v[54:55], v[194:195] op_sel_hi:[1,0]
	v_pk_mul_f32 v[56:57], v[56:57], v[194:195] op_sel:[0,1] op_sel_hi:[1,1]
	v_pk_mul_f32 v[58:59], v[58:59], v[194:195] op_sel:[0,1] op_sel_hi:[1,1]
	v_cvt_pk_bf16_f32 v52, v52, v56
	v_cvt_pk_bf16_f32 v53, v53, v57
	v_cvt_pk_bf16_f32 v54, v54, v58
	v_cvt_pk_bf16_f32 v55, v55, v59
	ds_write_b64 v5, v[52:53] offset:2112
	ds_write_b64 v5, v[54:55] offset:2120
	v_pk_mul_f32 v[60:61], v[60:61], v[196:197] op_sel_hi:[1,0]
	v_pk_mul_f32 v[62:63], v[62:63], v[196:197] op_sel_hi:[1,0]
	v_pk_mul_f32 v[64:65], v[64:65], v[196:197] op_sel:[0,1] op_sel_hi:[1,1]
	v_pk_mul_f32 v[66:67], v[66:67], v[196:197] op_sel:[0,1] op_sel_hi:[1,1]
	v_cvt_pk_bf16_f32 v60, v60, v64
	v_cvt_pk_bf16_f32 v61, v61, v65
	v_cvt_pk_bf16_f32 v62, v62, v66
	v_cvt_pk_bf16_f32 v63, v63, v67
	ds_write_b64 v5, v[60:61] offset:3168
	ds_write_b64 v5, v[62:63] offset:3176
	v_pk_mul_f32 v[68:69], v[68:69], v[198:199] op_sel_hi:[1,0]
	v_pk_mul_f32 v[70:71], v[70:71], v[198:199] op_sel_hi:[1,0]
	v_pk_mul_f32 v[72:73], v[72:73], v[198:199] op_sel:[0,1] op_sel_hi:[1,1]
	v_pk_mul_f32 v[74:75], v[74:75], v[198:199] op_sel:[0,1] op_sel_hi:[1,1]
	v_cvt_pk_bf16_f32 v68, v68, v72
	v_cvt_pk_bf16_f32 v69, v69, v73
	v_cvt_pk_bf16_f32 v70, v70, v74
	v_cvt_pk_bf16_f32 v71, v71, v75
	ds_write_b64 v5, v[68:69] offset:4224
	ds_write_b64 v5, v[70:71] offset:4232
	v_pk_mul_f32 v[76:77], v[76:77], v[200:201] op_sel_hi:[1,0]
	v_pk_mul_f32 v[78:79], v[78:79], v[200:201] op_sel_hi:[1,0]
	v_pk_mul_f32 v[80:81], v[80:81], v[200:201] op_sel:[0,1] op_sel_hi:[1,1]
	v_pk_mul_f32 v[82:83], v[82:83], v[200:201] op_sel:[0,1] op_sel_hi:[1,1]
	v_cvt_pk_bf16_f32 v76, v76, v80
	v_cvt_pk_bf16_f32 v77, v77, v81
	v_cvt_pk_bf16_f32 v78, v78, v82
	v_cvt_pk_bf16_f32 v79, v79, v83
	ds_write_b64 v5, v[76:77] offset:5280
	ds_write_b64 v5, v[78:79] offset:5288
	v_pk_mul_f32 v[84:85], v[84:85], v[202:203] op_sel_hi:[1,0]
	v_pk_mul_f32 v[86:87], v[86:87], v[202:203] op_sel_hi:[1,0]
	v_pk_mul_f32 v[88:89], v[88:89], v[202:203] op_sel:[0,1] op_sel_hi:[1,1]
	v_pk_mul_f32 v[90:91], v[90:91], v[202:203] op_sel:[0,1] op_sel_hi:[1,1]
	v_cvt_pk_bf16_f32 v84, v84, v88
	v_cvt_pk_bf16_f32 v85, v85, v89
	v_cvt_pk_bf16_f32 v86, v86, v90
	v_cvt_pk_bf16_f32 v87, v87, v91
	ds_write_b64 v5, v[84:85] offset:6336
	ds_write_b64 v5, v[86:87] offset:6344
	v_pk_mul_f32 v[92:93], v[92:93], v[204:205] op_sel_hi:[1,0]
	v_pk_mul_f32 v[94:95], v[94:95], v[204:205] op_sel_hi:[1,0]
	v_pk_mul_f32 v[96:97], v[96:97], v[204:205] op_sel:[0,1] op_sel_hi:[1,1]
	v_pk_mul_f32 v[98:99], v[98:99], v[204:205] op_sel:[0,1] op_sel_hi:[1,1]
	v_cvt_pk_bf16_f32 v92, v92, v96
	v_cvt_pk_bf16_f32 v93, v93, v97
	v_cvt_pk_bf16_f32 v94, v94, v98
	v_cvt_pk_bf16_f32 v95, v95, v99
	ds_write_b64 v5, v[92:93] offset:7392
	ds_write_b64 v5, v[94:95] offset:7400
	s_waitcnt lgkmcnt(0)
	ds_read2_b32 v[214:215], v6 offset0:0 offset1:66
	ds_read2_b32 v[216:217], v6 offset0:132 offset1:198
	ds_read2_b32 v[218:219], v6 offset0:8 offset1:74
	ds_read2_b32 v[220:221], v6 offset0:140 offset1:206
	ds_read2_b32 v[222:223], v6 offset0:16 offset1:82
	ds_read2_b32 v[224:225], v6 offset0:148 offset1:214
	ds_read2_b32 v[226:227], v6 offset0:24 offset1:90
	ds_read2_b32 v[228:229], v6 offset0:156 offset1:222
	ds_read2_b32 v[230:231], v6 offset0:32 offset1:98
	ds_read2_b32 v[232:233], v6 offset0:164 offset1:230
	ds_read2_b32 v[234:235], v6 offset0:40 offset1:106
	ds_read2_b32 v[236:237], v6 offset0:172 offset1:238
	ds_read2_b32 v[238:239], v6 offset0:48 offset1:114
	ds_read2_b32 v[240:241], v6 offset0:180 offset1:246
	ds_read2_b32 v[242:243], v6 offset0:56 offset1:122
	ds_read2_b32 v[244:245], v6 offset0:188 offset1:254
	s_waitcnt lgkmcnt(14)
	global_store_dwordx4 v7, v[214:217], s[40:41]
	s_add_u32 s40, s40, s42
	s_addc_u32 s41, s41, 0
	s_waitcnt lgkmcnt(12)
	global_store_dwordx4 v7, v[218:221], s[40:41]
	s_add_u32 s40, s40, s42
	s_addc_u32 s41, s41, 0
	s_waitcnt lgkmcnt(10)
	global_store_dwordx4 v7, v[222:225], s[40:41]
	s_add_u32 s40, s40, s42
	s_addc_u32 s41, s41, 0
	s_waitcnt lgkmcnt(8)
	global_store_dwordx4 v7, v[226:229], s[40:41]
	s_add_u32 s40, s40, s42
	s_addc_u32 s41, s41, 0
	s_waitcnt lgkmcnt(6)
	global_store_dwordx4 v7, v[230:233], s[40:41]
	s_add_u32 s40, s40, s42
	s_addc_u32 s41, s41, 0
	s_waitcnt lgkmcnt(4)
	global_store_dwordx4 v7, v[234:237], s[40:41]
	s_add_u32 s40, s40, s42
	s_addc_u32 s41, s41, 0
	s_waitcnt lgkmcnt(2)
	global_store_dwordx4 v7, v[238:241], s[40:41]
	s_add_u32 s40, s40, s42
	s_addc_u32 s41, s41, 0
	s_waitcnt lgkmcnt(0)
	global_store_dwordx4 v7, v[242:245], s[40:41]
	s_branch .Lcv_exit
.Lcv_slastB:
	s_waitcnt vmcnt(0)
	v_pk_mul_f32 v[100:101], v[100:101], v[18:19] op_sel_hi:[1,0]
	v_pk_mul_f32 v[102:103], v[102:103], v[18:19] op_sel_hi:[1,0]
	v_pk_mul_f32 v[104:105], v[104:105], v[18:19] op_sel:[0,1] op_sel_hi:[1,1]
	v_pk_mul_f32 v[106:107], v[106:107], v[18:19] op_sel:[0,1] op_sel_hi:[1,1]
	v_cvt_pk_bf16_f32 v100, v100, v104
	v_cvt_pk_bf16_f32 v101, v101, v105
	v_cvt_pk_bf16_f32 v102, v102, v106
	v_cvt_pk_bf16_f32 v103, v103, v107
	ds_write_b64 v5, v[100:101] offset:0
	ds_write_b64 v5, v[102:103] offset:8
	v_pk_mul_f32 v[108:109], v[108:109], v[20:21] op_sel_hi:[1,0]
	v_pk_mul_f32 v[110:111], v[110:111], v[20:21] op_sel_hi:[1,0]
	v_pk_mul_f32 v[112:113], v[112:113], v[20:21] op_sel:[0,1] op_sel_hi:[1,1]
	v_pk_mul_f32 v[114:115], v[114:115], v[20:21] op_sel:[0,1] op_sel_hi:[1,1]
	v_cvt_pk_bf16_f32 v108, v108, v112
	v_cvt_pk_bf16_f32 v109, v109, v113
	v_cvt_pk_bf16_f32 v110, v110, v114
	v_cvt_pk_bf16_f32 v111, v111, v115
	ds_write_b64 v5, v[108:109] offset:1056
	ds_write_b64 v5, v[110:111] offset:1064
	v_pk_mul_f32 v[116:117], v[116:117], v[22:23] op_sel_hi:[1,0]
	v_pk_mul_f32 v[118:119], v[118:119], v[22:23] op_sel_hi:[1,0]
	v_pk_mul_f32 v[120:121], v[120:121], v[22:23] op_sel:[0,1] op_sel_hi:[1,1]
	v_pk_mul_f32 v[122:123], v[122:123], v[22:23] op_sel:[0,1] op_sel_hi:[1,1]
	v_cvt_pk_bf16_f32 v116, v116, v120
	v_cvt_pk_bf16_f32 v117, v117, v121
	v_cvt_pk_bf16_f32 v118, v118, v122
	v_cvt_pk_bf16_f32 v119, v119, v123
	ds_write_b64 v5, v[116:117] offset:2112
	ds_write_b64 v5, v[118:119] offset:2120
	v_pk_mul_f32 v[124:125], v[124:125], v[24:25] op_sel_hi:[1,0]
	v_pk_mul_f32 v[126:127], v[126:127], v[24:25] op_sel_hi:[1,0]
	v_pk_mul_f32 v[128:129], v[128:129], v[24:25] op_sel:[0,1] op_sel_hi:[1,1]
	v_pk_mul_f32 v[130:131], v[130:131], v[24:25] op_sel:[0,1] op_sel_hi:[1,1]
	v_cvt_pk_bf16_f32 v124, v124, v128
	v_cvt_pk_bf16_f32 v125, v125, v129
	v_cvt_pk_bf16_f32 v126, v126, v130
	v_cvt_pk_bf16_f32 v127, v127, v131
	ds_write_b64 v5, v[124:125] offset:3168
	ds_write_b64 v5, v[126:127] offset:3176
	v_pk_mul_f32 v[132:133], v[132:133], v[26:27] op_sel_hi:[1,0]
	v_pk_mul_f32 v[134:135], v[134:135], v[26:27] op_sel_hi:[1,0]
	v_pk_mul_f32 v[136:137], v[136:137], v[26:27] op_sel:[0,1] op_sel_hi:[1,1]
	v_pk_mul_f32 v[138:139], v[138:139], v[26:27] op_sel:[0,1] op_sel_hi:[1,1]
	v_cvt_pk_bf16_f32 v132, v132, v136
	v_cvt_pk_bf16_f32 v133, v133, v137
	v_cvt_pk_bf16_f32 v134, v134, v138
	v_cvt_pk_bf16_f32 v135, v135, v139
	ds_write_b64 v5, v[132:133] offset:4224
	ds_write_b64 v5, v[134:135] offset:4232
	v_pk_mul_f32 v[140:141], v[140:141], v[28:29] op_sel_hi:[1,0]
	v_pk_mul_f32 v[142:143], v[142:143], v[28:29] op_sel_hi:[1,0]
	v_pk_mul_f32 v[144:145], v[144:145], v[28:29] op_sel:[0,1] op_sel_hi:[1,1]
	v_pk_mul_f32 v[146:147], v[146:147], v[28:29] op_sel:[0,1] op_sel_hi:[1,1]
	v_cvt_pk_bf16_f32 v140, v140, v144
	v_cvt_pk_bf16_f32 v141, v141, v145
	v_cvt_pk_bf16_f32 v142, v142, v146
	v_cvt_pk_bf16_f32 v143, v143, v147
	ds_write_b64 v5, v[140:141] offset:5280
	ds_write_b64 v5, v[142:143] offset:5288
	v_pk_mul_f32 v[148:149], v[148:149], v[30:31] op_sel_hi:[1,0]
	v_pk_mul_f32 v[150:151], v[150:151], v[30:31] op_sel_hi:[1,0]
	v_pk_mul_f32 v[152:153], v[152:153], v[30:31] op_sel:[0,1] op_sel_hi:[1,1]
	v_pk_mul_f32 v[154:155], v[154:155], v[30:31] op_sel:[0,1] op_sel_hi:[1,1]
	v_cvt_pk_bf16_f32 v148, v148, v152
	v_cvt_pk_bf16_f32 v149, v149, v153
	v_cvt_pk_bf16_f32 v150, v150, v154
	v_cvt_pk_bf16_f32 v151, v151, v155
	ds_write_b64 v5, v[148:149] offset:6336
	ds_write_b64 v5, v[150:151] offset:6344
	v_pk_mul_f32 v[156:157], v[156:157], v[32:33] op_sel_hi:[1,0]
	v_pk_mul_f32 v[158:159], v[158:159], v[32:33] op_sel_hi:[1,0]
	v_pk_mul_f32 v[160:161], v[160:161], v[32:33] op_sel:[0,1] op_sel_hi:[1,1]
	v_pk_mul_f32 v[162:163], v[162:163], v[32:33] op_sel:[0,1] op_sel_hi:[1,1]
	v_cvt_pk_bf16_f32 v156, v156, v160
	v_cvt_pk_bf16_f32 v157, v157, v161
	v_cvt_pk_bf16_f32 v158, v158, v162
	v_cvt_pk_bf16_f32 v159, v159, v163
	ds_write_b64 v5, v[156:157] offset:7392
	ds_write_b64 v5, v[158:159] offset:7400
	s_waitcnt lgkmcnt(0)
	ds_read2_b32 v[214:215], v6 offset0:0 offset1:66
	ds_read2_b32 v[216:217], v6 offset0:132 offset1:198
	ds_read2_b32 v[218:219], v6 offset0:8 offset1:74
	ds_read2_b32 v[220:221], v6 offset0:140 offset1:206
	ds_read2_b32 v[222:223], v6 offset0:16 offset1:82
	ds_read2_b32 v[224:225], v6 offset0:148 offset1:214
	ds_read2_b32 v[226:227], v6 offset0:24 offset1:90
	ds_read2_b32 v[228:229], v6 offset0:156 offset1:222
	ds_read2_b32 v[230:231], v6 offset0:32 offset1:98
	ds_read2_b32 v[232:233], v6 offset0:164 offset1:230
	ds_read2_b32 v[234:235], v6 offset0:40 offset1:106
	ds_read2_b32 v[236:237], v6 offset0:172 offset1:238
	ds_read2_b32 v[238:239], v6 offset0:48 offset1:114
	ds_read2_b32 v[240:241], v6 offset0:180 offset1:246
	ds_read2_b32 v[242:243], v6 offset0:56 offset1:122
	ds_read2_b32 v[244:245], v6 offset0:188 offset1:254
	s_waitcnt lgkmcnt(14)
	global_store_dwordx4 v12, v[214:217], s[44:45]
	s_add_u32 s44, s44, s46
	s_addc_u32 s45, s45, 0
	s_waitcnt lgkmcnt(12)
	global_store_dwordx4 v12, v[218:221], s[44:45]
	s_add_u32 s44, s44, s46
	s_addc_u32 s45, s45, 0
	s_waitcnt lgkmcnt(10)
	global_store_dwordx4 v12, v[222:225], s[44:45]
	s_add_u32 s44, s44, s46
	s_addc_u32 s45, s45, 0
	s_waitcnt lgkmcnt(8)
	global_store_dwordx4 v12, v[226:229], s[44:45]
	s_add_u32 s44, s44, s46
	s_addc_u32 s45, s45, 0
	s_waitcnt lgkmcnt(6)
	global_store_dwordx4 v12, v[230:233], s[44:45]
	s_add_u32 s44, s44, s46
	s_addc_u32 s45, s45, 0
	s_waitcnt lgkmcnt(4)
	global_store_dwordx4 v12, v[234:237], s[44:45]
	s_add_u32 s44, s44, s46
	s_addc_u32 s45, s45, 0
	s_waitcnt lgkmcnt(2)
	global_store_dwordx4 v12, v[238:241], s[44:45]
	s_add_u32 s44, s44, s46
	s_addc_u32 s45, s45, 0
	s_waitcnt lgkmcnt(0)
	global_store_dwordx4 v12, v[242:245], s[44:45]
.Lcv_exit0:
.Lcv_exit:
	s_waitcnt vmcnt(0) lgkmcnt(0)
	v_readlane_b32 s4, v254, 0
	v_readlane_b32 s5, v254, 1
	v_readlane_b32 s6, v254, 2
	v_readlane_b32 s7, v254, 3
	v_readlane_b32 s8, v254, 4
	v_readlane_b32 s9, v254, 5
	v_readlane_b32 s10, v254, 6
	v_readlane_b32 s11, v254, 7
	v_readlane_b32 s12, v254, 8
	v_readlane_b32 s13, v254, 9
	v_readlane_b32 s14, v254, 10
	v_readlane_b32 s15, v254, 11
	v_readlane_b32 s16, v254, 12
	v_readlane_b32 s17, v254, 13
	v_readlane_b32 s18, v254, 14
	v_readlane_b32 s19, v254, 15
	v_readlane_b32 s20, v254, 16
	v_readlane_b32 s21, v254, 17
	v_readlane_b32 s22, v254, 18
	v_readlane_b32 s23, v254, 19
	v_readlane_b32 s24, v254, 20
	v_readlane_b32 s25, v254, 21
	v_readlane_b32 s26, v254, 22
	v_readlane_b32 s27, v254, 23
	v_readlane_b32 s28, v254, 24
	v_readlane_b32 s29, v254, 25
	v_readlane_b32 s30, v254, 26
	v_readlane_b32 s31, v254, 27
	v_readlane_b32 s32, v254, 28
	v_readlane_b32 s33, v254, 29
	v_readlane_b32 s34, v254, 30
	v_readlane_b32 s35, v254, 31
	v_readlane_b32 s36, v254, 32
	v_readlane_b32 s37, v254, 33
	v_readlane_b32 s38, v254, 34
	v_readlane_b32 s39, v254, 35
	v_readlane_b32 s40, v254, 36
	v_readlane_b32 s41, v254, 37
	v_readlane_b32 s42, v254, 38
	v_readlane_b32 s43, v254, 39
	v_readlane_b32 s44, v254, 40
	v_readlane_b32 s45, v254, 41
	v_readlane_b32 s46, v254, 42
	v_readlane_b32 s47, v254, 43
	v_readlane_b32 s48, v254, 44
	v_readlane_b32 s49, v254, 45
	v_readlane_b32 s50, v254, 46
	v_readlane_b32 s51, v254, 47
	v_readlane_b32 s52, v254, 48
	v_readlane_b32 s53, v254, 49
	s_nop 4
	s_cmp_eq_u32 s98, 0
	s_cbranch_scc1 .Lcv_ret0
	s_cmp_eq_u32 s98, 1
	s_cbranch_scc1 .Lcv_ret1
	s_cmp_eq_u32 s98, 2
	s_cbranch_scc1 .Lcv_ret2
	s_cmp_eq_u32 s98, 3
	s_cbranch_scc1 .Lcv_ret3
	s_branch .Lcv_ret4
.Lcv_ret2:
.LBB0_911:
	v_readlane_b32 s0, v252, 50
	s_add_i32 s6, s0, 3
	s_cmp_lt_i32 s6, s63
	v_readlane_b32 s4, v252, 53
	s_cselect_b64 s[0:1], -1, 0
	v_readlane_b32 s5, v252, 54
	s_and_b64 s[4:5], s[4:5], s[0:1]
	s_andn2_b64 vcc, exec, s[4:5]
	s_cbranch_vccnz .LBB0_961
	s_waitcnt vmcnt(0)
	s_waitcnt vmcnt(0)
	s_barrier
	s_mov_b64 s[4:5], exec
	s_waitcnt lgkmcnt(0)
	v_readlane_b32 s8, v252, 43
	v_readlane_b32 s9, v252, 44
	s_and_b64 s[8:9], s[4:5], s[8:9]
	s_mov_b64 exec, s[8:9]
	s_cbranch_execz .LBB0_960
	v_readlane_b32 s8, v253, 2
	s_waitcnt vmcnt(0) expcnt(0) lgkmcnt(0)
	s_nop 0
	v_mov_b32_e32 v2, s8
	ds_read_b32 v4, v2
	ds_read_b32 v2, v2 offset:4
	s_waitcnt lgkmcnt(1)
	v_cmp_ne_u32_e32 vcc, 0, v4
	s_cbranch_vccnz .LBB0_928
	v_readlane_b32 s10, v253, 0
	v_readlane_b32 s11, v253, 1
	s_load_dwordx2 s[8:9], s[10:11], 0x4
	s_mov_b32 s16, 1
	s_waitcnt lgkmcnt(0)
	s_mul_i32 s14, s8, s3
	s_mul_i32 s14, s14, s9
	s_branch .LBB0_916

.LBB0_1670:
	s_waitcnt vmcnt(0)
	s_barrier
	s_mov_b32 s98, 4
	s_branch .Lcv_entry
.Lcv_ret4:
.LBB0_1671:
	v_readlane_b32 s0, v252, 50
	s_add_i32 s6, s0, 9
	s_cmp_ge_i32 s6, s63
	s_cbranch_scc1 .LBB0_1721
	s_waitcnt vmcnt(0)
	s_barrier
	s_mov_b64 s[0:1], exec
	v_readlane_b32 s4, v252, 43
	v_readlane_b32 s5, v252, 44
	s_and_b64 s[4:5], s[0:1], s[4:5]
	s_mov_b64 exec, s[4:5]
	s_cbranch_execz .LBB0_1720
	v_readlane_b32 s4, v253, 2
	s_waitcnt vmcnt(0) expcnt(0) lgkmcnt(0)
	s_nop 0
	v_mov_b32_e32 v2, s4
	ds_read_b32 v4, v2
	ds_read_b32 v2, v2 offset:4
	s_waitcnt lgkmcnt(1)
	v_cmp_ne_u32_e32 vcc, 0, v4
	s_cbranch_vccnz .LBB0_1688
	v_readlane_b32 s8, v253, 0
	v_readlane_b32 s9, v253, 1
	s_load_dwordx2 s[4:5], s[8:9], 0x4
	s_mov_b32 s13, 1
	s_waitcnt lgkmcnt(0)
	s_mul_i32 s12, s4, s3
	s_mul_i32 s12, s12, s5
	s_branch .LBB0_1676

.Lpost_getpc0:
	s_add_u32 s98, s98, (.LBB0_291-.Lpost_getpc0)&4294967295
	s_addc_u32 s99, s99, (.LBB0_291-.Lpost_getpc0)>>32
	s_setpc_b64 s[98:99]
.LBB0_1921:
	s_endpgm

	.amdhsa_kernel _Z3fwd4Args
		.amdhsa_group_segment_fixed_size 0
		.amdhsa_private_segment_fixed_size 0
		.amdhsa_kernarg_size 464
		.amdhsa_user_sgpr_count 2
		.amdhsa_user_sgpr_dispatch_ptr 0
		.amdhsa_user_sgpr_queue_ptr 0
		.amdhsa_user_sgpr_kernarg_segment_ptr 1
		.amdhsa_user_sgpr_dispatch_id 0
		.amdhsa_user_sgpr_kernarg_preload_length 0
		.amdhsa_user_sgpr_kernarg_preload_offset 0
		.amdhsa_user_sgpr_private_segment_size 0
		.amdhsa_uses_dynamic_stack 0
		.amdhsa_enable_private_segment 0
		.amdhsa_system_sgpr_workgroup_id_x 1
		.amdhsa_system_sgpr_workgroup_id_y 0
		.amdhsa_system_sgpr_workgroup_id_z 0
		.amdhsa_system_sgpr_workgroup_info 0
		.amdhsa_system_vgpr_workitem_id 0
		.amdhsa_next_free_vgpr 256
		.amdhsa_next_free_sgpr 100
		.amdhsa_accum_offset 256
		.amdhsa_reserve_vcc 1
		.amdhsa_float_round_mode_32 0
		.amdhsa_float_round_mode_16_64 0
		.amdhsa_float_denorm_mode_32 3
		.amdhsa_float_denorm_mode_16_64 3
		.amdhsa_dx10_clamp 1
		.amdhsa_ieee_mode 1
		.amdhsa_fp16_overflow 0
		.amdhsa_tg_split 0
		.amdhsa_exception_fp_ieee_invalid_op 0
		.amdhsa_exception_fp_denorm_src 0
		.amdhsa_exception_fp_ieee_div_zero 0
		.amdhsa_exception_fp_ieee_overflow 0
		.amdhsa_exception_fp_ieee_underflow 0
		.amdhsa_exception_fp_ieee_inexact 0
		.amdhsa_exception_int_div_zero 0
	.end_amdhsa_kernel

amdhsa.kernels:
  - .agpr_count:     0
    .args:
      - .offset:         0
        .size:           208
        .value_kind:     by_value
      - .offset:         208
        .size:           4
        .value_kind:     hidden_block_count_x
      - .offset:         212
        .size:           4
        .value_kind:     hidden_block_count_y
      - .offset:         216
        .size:           4
        .value_kind:     hidden_block_count_z
      - .offset:         220
        .size:           2
        .value_kind:     hidden_group_size_x
      - .offset:         222
        .size:           2
        .value_kind:     hidden_group_size_y
      - .offset:         224
        .size:           2
        .value_kind:     hidden_group_size_z
      - .offset:         226
        .size:           2
        .value_kind:     hidden_remainder_x
      - .offset:         228
        .size:           2
        .value_kind:     hidden_remainder_y
      - .offset:         230
        .size:           2
        .value_kind:     hidden_remainder_z
      - .offset:         248
        .size:           8
        .value_kind:     hidden_global_offset_x
      - .offset:         256
        .size:           8
        .value_kind:     hidden_global_offset_y
      - .offset:         264
        .size:           8
        .value_kind:     hidden_global_offset_z
      - .offset:         272
        .size:           2
        .value_kind:     hidden_grid_dims
      - .offset:         328
        .size:           4
        .value_kind:     hidden_dynamic_lds_size
    .group_segment_fixed_size: 0
    .kernarg_segment_align: 8
    .kernarg_segment_size: 464
    .language:       OpenCL C
    .language_version:
      - 2
      - 0
    .max_flat_workgroup_size: 512
    .name:           _Z3fwd4Args
    .private_segment_fixed_size: 0
    .sgpr_count:     106
    .sgpr_spill_count: 125
    .symbol:         _Z3fwd4Args.kd
    .uniform_work_group_size: 1
    .uses_dynamic_stack: false
    .vgpr_count:     256
    .vgpr_spill_count: 0
    .wavefront_size: 64
